# w_in GEMM: mixed schedule, one shared-A tile pair plus at most one single tile per workgroup
# speedup vs baseline: 1.0411x; 1.0059x over previous
.LBB0_488:
	v_mov_b32_e32 v2, v0
	s_mov_b32 s6, s2
	s_cmpk_gt_i32 s6, 0x33f
	s_cbranch_scc1 .LBB0_499
	v_ashrrev_i32_e32 v3, 6, v2
	v_lshlrev_b32_e32 v7, 2, v3
	v_and_b32_e32 v7, 4, v7
	v_bfe_u32 v8, v2, 4, 2
	v_and_b32_e32 v9, 7, v2
	v_bfe_u32 v4, v2, 3, 3
	v_bitop3_b32 v7, v7, v9, v8 bitop3:0x36
	v_lshl_or_b32 v80, v3, 3, v4
	v_lshrrev_b32_e32 v4, 1, v2
	v_bfe_u32 v5, v2, 1, 3
	v_bfe_u32 v6, v2, 5, 1
	v_ashrrev_i32_e32 v8, 7, v2
	v_and_b32_e32 v2, 31, v2
	v_lshlrev_b32_e32 v130, 4, v7
	v_readlane_b32 s0, v253, 14
	v_lshlrev_b32_e32 v7, 5, v3
	v_readlane_b32 s1, v253, 15
	v_lshlrev_b32_e32 v81, 6, v8
	v_lshl_add_u32 v83, v3, 10, 0
	v_bitop3_b32 v3, v6, v4, 7 bitop3:0x78
	v_lshlrev_b32_e32 v4, 13, v8
	v_lshlrev_b32_e32 v8, 7, v2
	v_and_or_b32 v84, v7, 32, v2
	v_bitop3_b32 v2, v6, v5, 2 bitop3:0x36
	v_bitop3_b32 v7, v6, v5, 4 bitop3:0x36
	v_bitop3_b32 v5, v6, v5, 6 bitop3:0x36
	v_lshl_add_u64 v[66:67], s[0:1], 0, v[130:131]
	v_readlane_b32 s0, v254, 62
	v_lshl_add_u32 v116, v5, 4, 0
	v_lshl_add_u32 v117, v7, 4, 0
	v_lshl_add_u32 v118, v2, 4, 0
	v_lshl_add_u32 v119, v3, 4, 0
	v_readlane_b32 s1, v254, 63
	v_lshlrev_b32_e32 v82, 2, v6
	v_add_u32_e32 v5, v116, v4
	v_add_u32_e32 v6, v117, v4
	v_add_u32_e32 v2, v118, v4
	v_add_u32_e32 v3, v119, v4
	v_lshl_add_u64 v[68:69], s[0:1], 0, v[130:131]
	v_lshlrev_b32_e32 v85, 7, v84
	v_or_b32_e32 v86, 1, v82
	v_or_b32_e32 v87, 2, v82
	v_or_b32_e32 v88, 3, v82
	v_or_b32_e32 v89, 8, v82
	v_or_b32_e32 v90, 9, v82
	v_or_b32_e32 v91, 10, v82
	v_or_b32_e32 v92, 11, v82
	v_or_b32_e32 v93, 16, v82
	v_or_b32_e32 v94, 17, v82
	v_or_b32_e32 v95, 18, v82
	v_or_b32_e32 v96, 19, v82
	v_or_b32_e32 v97, 24, v82
	v_or_b32_e32 v98, 25, v82
	v_or_b32_e32 v99, 26, v82
	v_or_b32_e32 v100, 27, v82
	v_or_b32_e32 v101, 33, v82
	v_or_b32_e32 v102, 34, v82
	v_or_b32_e32 v103, 35, v82
	v_or_b32_e32 v104, 40, v82
	v_or_b32_e32 v105, 41, v82
	v_or_b32_e32 v106, 42, v82
	v_or_b32_e32 v107, 43, v82
	v_or_b32_e32 v108, 48, v82
	v_or_b32_e32 v109, 49, v82
	v_or_b32_e32 v110, 50, v82
	v_or_b32_e32 v111, 51, v82
	v_or_b32_e32 v112, 56, v82
	v_or_b32_e32 v113, 57, v82
	v_or_b32_e32 v114, 58, v82
	v_or_b32_e32 v115, 59, v82
	v_add_u32_e32 v120, v3, v8
	v_add_u32_e32 v121, v2, v8
	v_add_u32_e32 v122, v6, v8
	v_add_u32_e32 v123, v5, v8
	v_writelane_b32 v255, s6, 47
	v_mov_b32_e32 v196, 0x12ff0
	ds_read_b32 v205, v196 offset:4
	ds_read_b32 v196, v196
	s_waitcnt lgkmcnt(0)
	s_branch .Lg0_item
.LBB0_490:
	s_or_b64 exec, exec, s[4:5]
	v_readlane_b32 s0, v255, 48
	s_cmp_eq_u32 s0, 1
	s_cbranch_scc0 .Lg0_adv
	s_mov_b32 s0, 0
	s_nop 0
	v_writelane_b32 v255, s0, 48
	v_mov_b32_e32 v50, v164
	v_mov_b32_e32 v51, v165
	v_mov_b32_e32 v52, v166
	v_mov_b32_e32 v53, v167
	v_mov_b32_e32 v54, v168
	v_mov_b32_e32 v55, v169
	v_mov_b32_e32 v56, v170
	v_mov_b32_e32 v57, v171
	v_mov_b32_e32 v58, v172
	v_mov_b32_e32 v59, v173
	v_mov_b32_e32 v60, v174
	v_mov_b32_e32 v61, v175
	v_mov_b32_e32 v62, v176
	v_mov_b32_e32 v63, v177
	v_mov_b32_e32 v64, v178
	v_mov_b32_e32 v65, v179
	v_mov_b32_e32 v34, v180
	v_mov_b32_e32 v35, v181
	v_mov_b32_e32 v36, v182
	v_mov_b32_e32 v37, v183
	v_mov_b32_e32 v38, v184
	v_mov_b32_e32 v39, v185
	v_mov_b32_e32 v40, v186
	v_mov_b32_e32 v41, v187
	v_mov_b32_e32 v42, v188
	v_mov_b32_e32 v43, v189
	v_mov_b32_e32 v44, v190
	v_mov_b32_e32 v45, v191
	v_mov_b32_e32 v46, v192
	v_mov_b32_e32 v47, v193
	v_mov_b32_e32 v48, v194
	v_mov_b32_e32 v49, v195
	v_mov_b32_e32 v18, v206
	v_mov_b32_e32 v19, v207
	v_mov_b32_e32 v20, v208
	v_mov_b32_e32 v21, v209
	v_mov_b32_e32 v22, v210
	v_mov_b32_e32 v23, v211
	v_mov_b32_e32 v24, v212
	v_mov_b32_e32 v25, v213
	v_mov_b32_e32 v26, v214
	v_mov_b32_e32 v27, v215
	v_mov_b32_e32 v28, v216
	v_mov_b32_e32 v29, v217
	v_mov_b32_e32 v30, v218
	v_mov_b32_e32 v31, v219
	v_mov_b32_e32 v32, v220
	v_mov_b32_e32 v33, v221
	v_mov_b32_e32 v2, v222
	v_mov_b32_e32 v3, v223
	v_mov_b32_e32 v4, v224
	v_mov_b32_e32 v5, v225
	v_mov_b32_e32 v6, v226
	v_mov_b32_e32 v7, v227
	v_mov_b32_e32 v8, v228
	v_mov_b32_e32 v9, v229
	v_mov_b32_e32 v10, v230
	v_mov_b32_e32 v11, v231
	v_mov_b32_e32 v12, v232
	v_mov_b32_e32 v13, v233
	v_mov_b32_e32 v14, v234
	v_mov_b32_e32 v15, v235
	v_mov_b32_e32 v16, v236
	v_mov_b32_e32 v17, v237
	s_lshl_b32 s1, s6, 1
	s_and_b32 s1, s1, 0xffffff80
	s_add_u32 s1, s1, 0x80
	s_lshl_b32 s0, s6, 7
	s_and_b32 s0, s0, 0x1f80
	s_branch .Lg0_epi
.Lg0_adv:
	v_readlane_b32 s6, v255, 47
	v_readlane_b32 s0, v252, 2
	v_readlane_b32 s1, v252, 3
	s_load_dword s0, s[0:1], 0x0
	s_waitcnt lgkmcnt(0)
	s_add_i32 s6, s0, s6
	s_cmpk_gt_i32 s6, 0x33f
	s_cbranch_scc1 .Lg0_exit
	v_writelane_b32 v255, s6, 47
	s_branch .Lg0_item
.Lg0_exit:
	v_mov_b32_e32 v2, 0x12ff0
	ds_write_b32 v2, v196
	ds_write_b32 v2, v205 offset:4
	s_waitcnt lgkmcnt(0)
	s_branch .LBB0_499
.Lg0_item:
	s_cmp_lt_u32 s6, 0x200
	s_cbranch_scc1 .Lg0_ispair
	s_add_u32 s6, s6, 0x200
	s_mov_b32 s0, 0
	s_branch .Lg0_setflag
.Lg0_ispair:
	s_lshr_b32 s0, s6, 6
	s_lshl_b32 s0, s0, 7
	s_and_b32 s6, s6, 63
	s_or_b32 s6, s6, s0
	s_mov_b32 s0, 1
.Lg0_setflag:
	s_nop 0
	v_writelane_b32 v255, s0, 48
.LBB0_491:
	s_lshl_b32 s1, s6, 1
	s_and_b32 s1, s1, 0xffffff80
	v_add_u32_e32 v6, s1, v80
	v_min_i32_e32 v4, 0xa2f, v6
	v_ashrrev_i32_e32 v5, 31, v4
	v_lshlrev_b64 v[4:5], 11, v[4:5]
	v_lshl_add_u64 v[70:71], v[68:69], 0, v[4:5]
	v_add_u32_e32 v4, 32, v6
	s_lshl_b32 s0, s6, 7
	v_min_i32_e32 v4, 0xa2f, v4
	s_and_b32 s0, s0, 0x1f80
	v_ashrrev_i32_e32 v5, 31, v4
	v_add_u32_e32 v2, s0, v80
	v_lshlrev_b64 v[4:5], 11, v[4:5]
	v_ashrrev_i32_e32 v3, 31, v2
	v_lshl_add_u64 v[72:73], v[68:69], 0, v[4:5]
	v_add_u32_e32 v4, 64, v6
	v_lshlrev_b64 v[2:3], 11, v[2:3]
	v_min_i32_e32 v4, 0xa2f, v4
	v_readfirstlane_b32 s22, v83
	v_add_u32_e32 v137, 0x8000, v83
	v_ashrrev_i32_e32 v5, 31, v4
	v_lshl_add_u64 v[78:79], v[66:67], 0, v[2:3]
	s_mov_b32 m0, s22
	v_readfirstlane_b32 s24, v137
	v_add_u32_e32 v138, 0x1000, v83
	v_lshlrev_b64 v[4:5], 11, v[4:5]
	global_load_lds_dwordx4 v[78:79], off
	s_mov_b32 m0, s24
	s_mov_b64 s[4:5], 0x10000
	v_readfirstlane_b32 s25, v138
	v_add_u32_e32 v139, 0x9000, v83
	v_lshl_add_u64 v[74:75], v[68:69], 0, v[4:5]
	v_add_u32_e32 v4, 0x60, v6
	global_load_lds_dwordx4 v[70:71], off
	v_lshl_add_u64 v[2:3], v[78:79], 0, s[4:5]
	s_mov_b32 m0, s25
	v_readfirstlane_b32 s27, v139
	v_add_u32_e32 v140, 0x2000, v83
	v_min_i32_e32 v4, 0xa2f, v4
	global_load_lds_dwordx4 v[2:3], off
	s_mov_b32 m0, s27
	s_mov_b64 s[4:5], 0x20000
	v_readfirstlane_b32 s36, v140
	v_add_u32_e32 v134, 0xa000, v83
	v_ashrrev_i32_e32 v5, 31, v4
	global_load_lds_dwordx4 v[72:73], off
	v_lshl_add_u64 v[2:3], v[78:79], 0, s[4:5]
	s_mov_b32 m0, s36
	v_readfirstlane_b32 s37, v134
	v_add_u32_e32 v136, 0x3000, v83
	v_lshlrev_b64 v[4:5], 11, v[4:5]
	global_load_lds_dwordx4 v[2:3], off
	s_mov_b32 m0, s37
	s_mov_b64 s[4:5], 0x30000
	v_readfirstlane_b32 s38, v136
	v_add_u32_e32 v135, 0xb000, v83
	v_lshl_add_u64 v[76:77], v[68:69], 0, v[4:5]
	global_load_lds_dwordx4 v[74:75], off
	v_lshl_add_u64 v[2:3], v[78:79], 0, s[4:5]
	s_mov_b32 m0, s38
	v_readfirstlane_b32 s39, v135
	v_add_u32_e32 v4, 0x4000, v83
	global_load_lds_dwordx4 v[2:3], off
	s_mov_b32 m0, s39
	v_readfirstlane_b32 s4, v4
	v_add_u32_e32 v4, 0xc000, v83
	global_load_lds_dwordx4 v[76:77], off
	v_lshl_add_u64 v[2:3], v[78:79], 0, s[98:99]
	s_mov_b32 m0, s4
	v_readfirstlane_b32 s5, v4
	v_add_u32_e32 v4, 0x5000, v83
	s_waitcnt vmcnt(0)
	s_waitcnt vmcnt(0) lgkmcnt(0)
	s_barrier
	v_readlane_b32 s24, v255, 48
	s_cmp_eq_u32 s24, 1
	s_cbranch_scc1 .Lg0_pair
	v_mov_b32_e32 v2, 0
	v_mov_b32_e32 v3, 0
	v_mov_b32_e32 v4, 0
	v_mov_b32_e32 v5, 0
	v_mov_b32_e32 v6, 0
	v_mov_b32_e32 v7, 0
	v_mov_b32_e32 v8, 0
	v_mov_b32_e32 v9, 0
	v_mov_b32_e32 v10, 0
	v_mov_b32_e32 v11, 0
	v_mov_b32_e32 v12, 0
	v_mov_b32_e32 v13, 0
	v_mov_b32_e32 v14, 0
	v_mov_b32_e32 v15, 0
	v_mov_b32_e32 v16, 0
	v_mov_b32_e32 v17, 0
	v_mov_b32_e32 v18, 0
	v_mov_b32_e32 v19, 0
	v_mov_b32_e32 v20, 0
	v_mov_b32_e32 v21, 0
	v_mov_b32_e32 v22, 0
	v_mov_b32_e32 v23, 0
	v_mov_b32_e32 v24, 0
	v_mov_b32_e32 v25, 0
	v_mov_b32_e32 v26, 0
	v_mov_b32_e32 v27, 0
	v_mov_b32_e32 v28, 0
	v_mov_b32_e32 v29, 0
	v_mov_b32_e32 v30, 0
	v_mov_b32_e32 v31, 0
	v_mov_b32_e32 v32, 0
	v_mov_b32_e32 v33, 0
	v_mov_b32_e32 v34, 0
	v_mov_b32_e32 v35, 0
	v_mov_b32_e32 v36, 0
	v_mov_b32_e32 v37, 0
	v_mov_b32_e32 v38, 0
	v_mov_b32_e32 v39, 0
	v_mov_b32_e32 v40, 0
	v_mov_b32_e32 v41, 0
	v_mov_b32_e32 v42, 0
	v_mov_b32_e32 v43, 0
	v_mov_b32_e32 v44, 0
	v_mov_b32_e32 v45, 0
	v_mov_b32_e32 v46, 0
	v_mov_b32_e32 v47, 0
	v_mov_b32_e32 v48, 0
	v_mov_b32_e32 v49, 0
	v_mov_b32_e32 v50, 0
	v_mov_b32_e32 v51, 0
	v_mov_b32_e32 v52, 0
	v_mov_b32_e32 v53, 0
	v_mov_b32_e32 v54, 0
	v_mov_b32_e32 v55, 0
	v_mov_b32_e32 v56, 0
	v_mov_b32_e32 v57, 0
	v_mov_b32_e32 v58, 0
	v_mov_b32_e32 v59, 0
	v_mov_b32_e32 v60, 0
	v_mov_b32_e32 v61, 0
	v_mov_b32_e32 v62, 0
	v_mov_b32_e32 v63, 0
	v_mov_b32_e32 v64, 0
	v_mov_b32_e32 v65, 0
	v_lshl_add_u64 v[164:165], v[78:79], 0, s[98:99]
	s_mov_b64 s[10:11], 0x10080
	v_lshl_add_u64 v[166:167], v[78:79], 0, s[10:11]
	s_mov_b64 s[10:11], 0x20080
	v_lshl_add_u64 v[168:169], v[78:79], 0, s[10:11]
	s_mov_b64 s[10:11], 0x30080
	v_lshl_add_u64 v[170:171], v[78:79], 0, s[10:11]
	v_lshl_add_u64 v[172:173], v[70:71], 0, s[98:99]
	v_lshl_add_u64 v[174:175], v[72:73], 0, s[98:99]
	v_lshl_add_u64 v[176:177], v[74:75], 0, s[98:99]
	v_lshl_add_u64 v[178:179], v[76:77], 0, s[98:99]
	v_add_u32_e32 v222, v119, v85
	v_add_u32_e32 v223, v118, v85
	v_add_u32_e32 v224, v117, v85
	v_add_u32_e32 v225, v116, v85
	s_mov_b32 s24, 7
	ds_read_b128 v[180:183], v120
	ds_read_b128 v[184:187], v120 offset:4096
	ds_read_b128 v[188:191], v222 offset:32768
	ds_read_b128 v[192:195], v222 offset:40960
.Lg0_loop:
	ds_read_b128 v[206:209], v121
	ds_read_b128 v[210:213], v121 offset:4096
	ds_read_b128 v[214:217], v223 offset:32768
	ds_read_b128 v[218:221], v223 offset:40960
	s_waitcnt lgkmcnt(4)
	v_mfma_f32_32x32x16_bf16 v[50:65], v[180:183], v[188:191], v[50:65]
	s_add_u32 m0, s22, 0x4000
	s_nop 0
	global_load_lds_dwordx4 v[164:165], off
	v_lshl_add_u64 v[164:165], v[164:165], 0, s[98:99]
	v_mfma_f32_32x32x16_bf16 v[34:49], v[180:183], v[192:195], v[34:49]
	s_add_u32 m0, s22, 0xc000
	s_nop 0
	global_load_lds_dwordx4 v[172:173], off
	v_lshl_add_u64 v[172:173], v[172:173], 0, s[98:99]
	v_mfma_f32_32x32x16_bf16 v[18:33], v[184:187], v[188:191], v[18:33]
	s_add_u32 m0, s22, 0x5000
	s_nop 0
	global_load_lds_dwordx4 v[166:167], off
	v_lshl_add_u64 v[166:167], v[166:167], 0, s[98:99]
	v_mfma_f32_32x32x16_bf16 v[2:17], v[184:187], v[192:195], v[2:17]
	ds_read_b128 v[180:183], v122
	ds_read_b128 v[184:187], v122 offset:4096
	ds_read_b128 v[188:191], v224 offset:32768
	ds_read_b128 v[192:195], v224 offset:40960
	s_waitcnt lgkmcnt(4)
	v_mfma_f32_32x32x16_bf16 v[50:65], v[206:209], v[214:217], v[50:65]
	s_add_u32 m0, s22, 0xd000
	s_nop 0
	global_load_lds_dwordx4 v[174:175], off
	v_lshl_add_u64 v[174:175], v[174:175], 0, s[98:99]
	v_mfma_f32_32x32x16_bf16 v[34:49], v[206:209], v[218:221], v[34:49]
	s_add_u32 m0, s22, 0x6000
	s_nop 0
	global_load_lds_dwordx4 v[168:169], off
	v_lshl_add_u64 v[168:169], v[168:169], 0, s[98:99]
	v_mfma_f32_32x32x16_bf16 v[18:33], v[210:213], v[214:217], v[18:33]
	s_add_u32 m0, s22, 0xe000
	s_nop 0
	global_load_lds_dwordx4 v[176:177], off
	v_lshl_add_u64 v[176:177], v[176:177], 0, s[98:99]
	v_mfma_f32_32x32x16_bf16 v[2:17], v[210:213], v[218:221], v[2:17]
	ds_read_b128 v[206:209], v123
	ds_read_b128 v[210:213], v123 offset:4096
	ds_read_b128 v[214:217], v225 offset:32768
	ds_read_b128 v[218:221], v225 offset:40960
	s_waitcnt lgkmcnt(4)
	v_mfma_f32_32x32x16_bf16 v[50:65], v[180:183], v[188:191], v[50:65]
	s_add_u32 m0, s22, 0x7000
	s_nop 0
	global_load_lds_dwordx4 v[170:171], off
	v_lshl_add_u64 v[170:171], v[170:171], 0, s[98:99]
	v_mfma_f32_32x32x16_bf16 v[34:49], v[180:183], v[192:195], v[34:49]
	s_add_u32 m0, s22, 0xf000
	s_nop 0
	global_load_lds_dwordx4 v[178:179], off
	v_lshl_add_u64 v[178:179], v[178:179], 0, s[98:99]
	v_mfma_f32_32x32x16_bf16 v[18:33], v[184:187], v[188:191], v[18:33]
	v_mfma_f32_32x32x16_bf16 v[2:17], v[184:187], v[192:195], v[2:17]
	s_waitcnt vmcnt(0) lgkmcnt(0)
	s_barrier
	ds_read_b128 v[180:183], v120 offset:16384
	ds_read_b128 v[184:187], v120 offset:20480
	ds_read_b128 v[188:191], v222 offset:49152
	ds_read_b128 v[192:195], v222 offset:57344
	v_mfma_f32_32x32x16_bf16 v[50:65], v[206:209], v[214:217], v[50:65]
	v_mfma_f32_32x32x16_bf16 v[34:49], v[206:209], v[218:221], v[34:49]
	v_mfma_f32_32x32x16_bf16 v[18:33], v[210:213], v[214:217], v[18:33]
	v_mfma_f32_32x32x16_bf16 v[2:17], v[210:213], v[218:221], v[2:17]
	ds_read_b128 v[206:209], v121 offset:16384
	ds_read_b128 v[210:213], v121 offset:20480
	ds_read_b128 v[214:217], v223 offset:49152
	ds_read_b128 v[218:221], v223 offset:57344
	s_waitcnt lgkmcnt(4)
	v_mfma_f32_32x32x16_bf16 v[50:65], v[180:183], v[188:191], v[50:65]
	s_mov_b32 m0, s22
	s_nop 0
	global_load_lds_dwordx4 v[164:165], off
	v_lshl_add_u64 v[164:165], v[164:165], 0, s[98:99]
	v_mfma_f32_32x32x16_bf16 v[34:49], v[180:183], v[192:195], v[34:49]
	s_add_u32 m0, s22, 0x8000
	s_nop 0
	global_load_lds_dwordx4 v[172:173], off
	v_lshl_add_u64 v[172:173], v[172:173], 0, s[98:99]
	v_mfma_f32_32x32x16_bf16 v[18:33], v[184:187], v[188:191], v[18:33]
	s_add_u32 m0, s22, 0x1000
	s_nop 0
	global_load_lds_dwordx4 v[166:167], off
	v_lshl_add_u64 v[166:167], v[166:167], 0, s[98:99]
	v_mfma_f32_32x32x16_bf16 v[2:17], v[184:187], v[192:195], v[2:17]
	ds_read_b128 v[180:183], v122 offset:16384
	ds_read_b128 v[184:187], v122 offset:20480
	ds_read_b128 v[188:191], v224 offset:49152
	ds_read_b128 v[192:195], v224 offset:57344
	s_waitcnt lgkmcnt(4)
	v_mfma_f32_32x32x16_bf16 v[50:65], v[206:209], v[214:217], v[50:65]
	s_add_u32 m0, s22, 0x9000
	s_nop 0
	global_load_lds_dwordx4 v[174:175], off
	v_lshl_add_u64 v[174:175], v[174:175], 0, s[98:99]
	v_mfma_f32_32x32x16_bf16 v[34:49], v[206:209], v[218:221], v[34:49]
	s_add_u32 m0, s22, 0x2000
	s_nop 0
	global_load_lds_dwordx4 v[168:169], off
	v_lshl_add_u64 v[168:169], v[168:169], 0, s[98:99]
	v_mfma_f32_32x32x16_bf16 v[18:33], v[210:213], v[214:217], v[18:33]
	s_add_u32 m0, s22, 0xa000
	s_nop 0
	global_load_lds_dwordx4 v[176:177], off
	v_lshl_add_u64 v[176:177], v[176:177], 0, s[98:99]
	v_mfma_f32_32x32x16_bf16 v[2:17], v[210:213], v[218:221], v[2:17]
	ds_read_b128 v[206:209], v123 offset:16384
	ds_read_b128 v[210:213], v123 offset:20480
	ds_read_b128 v[214:217], v225 offset:49152
	ds_read_b128 v[218:221], v225 offset:57344
	s_waitcnt lgkmcnt(4)
	v_mfma_f32_32x32x16_bf16 v[50:65], v[180:183], v[188:191], v[50:65]
	s_add_u32 m0, s22, 0x3000
	s_nop 0
	global_load_lds_dwordx4 v[170:171], off
	v_lshl_add_u64 v[170:171], v[170:171], 0, s[98:99]
	v_mfma_f32_32x32x16_bf16 v[34:49], v[180:183], v[192:195], v[34:49]
	s_add_u32 m0, s22, 0xb000
	s_nop 0
	global_load_lds_dwordx4 v[178:179], off
	v_lshl_add_u64 v[178:179], v[178:179], 0, s[98:99]
	v_mfma_f32_32x32x16_bf16 v[18:33], v[184:187], v[188:191], v[18:33]
	v_mfma_f32_32x32x16_bf16 v[2:17], v[184:187], v[192:195], v[2:17]
	s_waitcnt vmcnt(0) lgkmcnt(0)
	s_barrier
	ds_read_b128 v[180:183], v120
	ds_read_b128 v[184:187], v120 offset:4096
	ds_read_b128 v[188:191], v222 offset:32768
	ds_read_b128 v[192:195], v222 offset:40960
	v_mfma_f32_32x32x16_bf16 v[50:65], v[206:209], v[214:217], v[50:65]
	v_mfma_f32_32x32x16_bf16 v[34:49], v[206:209], v[218:221], v[34:49]
	v_mfma_f32_32x32x16_bf16 v[18:33], v[210:213], v[214:217], v[18:33]
	v_mfma_f32_32x32x16_bf16 v[2:17], v[210:213], v[218:221], v[2:17]
	s_sub_u32 s24, s24, 1
	s_cmp_lg_u32 s24, 0
	s_cbranch_scc1 .Lg0_loop
	ds_read_b128 v[206:209], v121
	ds_read_b128 v[210:213], v121 offset:4096
	ds_read_b128 v[214:217], v223 offset:32768
	ds_read_b128 v[218:221], v223 offset:40960
	s_waitcnt lgkmcnt(4)
	v_mfma_f32_32x32x16_bf16 v[50:65], v[180:183], v[188:191], v[50:65]
	s_add_u32 m0, s22, 0x4000
	s_nop 0
	global_load_lds_dwordx4 v[164:165], off
	v_lshl_add_u64 v[164:165], v[164:165], 0, s[98:99]
	v_mfma_f32_32x32x16_bf16 v[34:49], v[180:183], v[192:195], v[34:49]
	s_add_u32 m0, s22, 0xc000
	s_nop 0
	global_load_lds_dwordx4 v[172:173], off
	v_lshl_add_u64 v[172:173], v[172:173], 0, s[98:99]
	v_mfma_f32_32x32x16_bf16 v[18:33], v[184:187], v[188:191], v[18:33]
	s_add_u32 m0, s22, 0x5000
	s_nop 0
	global_load_lds_dwordx4 v[166:167], off
	v_lshl_add_u64 v[166:167], v[166:167], 0, s[98:99]
	v_mfma_f32_32x32x16_bf16 v[2:17], v[184:187], v[192:195], v[2:17]
	ds_read_b128 v[180:183], v122
	ds_read_b128 v[184:187], v122 offset:4096
	ds_read_b128 v[188:191], v224 offset:32768
	ds_read_b128 v[192:195], v224 offset:40960
	s_waitcnt lgkmcnt(4)
	v_mfma_f32_32x32x16_bf16 v[50:65], v[206:209], v[214:217], v[50:65]
	s_add_u32 m0, s22, 0xd000
	s_nop 0
	global_load_lds_dwordx4 v[174:175], off
	v_lshl_add_u64 v[174:175], v[174:175], 0, s[98:99]
	v_mfma_f32_32x32x16_bf16 v[34:49], v[206:209], v[218:221], v[34:49]
	s_add_u32 m0, s22, 0x6000
	s_nop 0
	global_load_lds_dwordx4 v[168:169], off
	v_lshl_add_u64 v[168:169], v[168:169], 0, s[98:99]
	v_mfma_f32_32x32x16_bf16 v[18:33], v[210:213], v[214:217], v[18:33]
	s_add_u32 m0, s22, 0xe000
	s_nop 0
	global_load_lds_dwordx4 v[176:177], off
	v_lshl_add_u64 v[176:177], v[176:177], 0, s[98:99]
	v_mfma_f32_32x32x16_bf16 v[2:17], v[210:213], v[218:221], v[2:17]
	ds_read_b128 v[206:209], v123
	ds_read_b128 v[210:213], v123 offset:4096
	ds_read_b128 v[214:217], v225 offset:32768
	ds_read_b128 v[218:221], v225 offset:40960
	s_waitcnt lgkmcnt(4)
	v_mfma_f32_32x32x16_bf16 v[50:65], v[180:183], v[188:191], v[50:65]
	s_add_u32 m0, s22, 0x7000
	s_nop 0
	global_load_lds_dwordx4 v[170:171], off
	v_lshl_add_u64 v[170:171], v[170:171], 0, s[98:99]
	v_mfma_f32_32x32x16_bf16 v[34:49], v[180:183], v[192:195], v[34:49]
	s_add_u32 m0, s22, 0xf000
	s_nop 0
	global_load_lds_dwordx4 v[178:179], off
	v_lshl_add_u64 v[178:179], v[178:179], 0, s[98:99]
	v_mfma_f32_32x32x16_bf16 v[18:33], v[184:187], v[188:191], v[18:33]
	v_mfma_f32_32x32x16_bf16 v[2:17], v[184:187], v[192:195], v[2:17]
	s_waitcnt vmcnt(0) lgkmcnt(0)
	s_barrier
	ds_read_b128 v[180:183], v120 offset:16384
	ds_read_b128 v[184:187], v120 offset:20480
	ds_read_b128 v[188:191], v222 offset:49152
	ds_read_b128 v[192:195], v222 offset:57344
	v_mfma_f32_32x32x16_bf16 v[50:65], v[206:209], v[214:217], v[50:65]
	v_mfma_f32_32x32x16_bf16 v[34:49], v[206:209], v[218:221], v[34:49]
	v_mfma_f32_32x32x16_bf16 v[18:33], v[210:213], v[214:217], v[18:33]
	v_mfma_f32_32x32x16_bf16 v[2:17], v[210:213], v[218:221], v[2:17]
	ds_read_b128 v[206:209], v121 offset:16384
	ds_read_b128 v[210:213], v121 offset:20480
	ds_read_b128 v[214:217], v223 offset:49152
	ds_read_b128 v[218:221], v223 offset:57344
	s_waitcnt lgkmcnt(4)
	v_mfma_f32_32x32x16_bf16 v[50:65], v[180:183], v[188:191], v[50:65]
	v_mfma_f32_32x32x16_bf16 v[34:49], v[180:183], v[192:195], v[34:49]
	v_mfma_f32_32x32x16_bf16 v[18:33], v[184:187], v[188:191], v[18:33]
	v_mfma_f32_32x32x16_bf16 v[2:17], v[184:187], v[192:195], v[2:17]
	ds_read_b128 v[180:183], v122 offset:16384
	ds_read_b128 v[184:187], v122 offset:20480
	ds_read_b128 v[188:191], v224 offset:49152
	ds_read_b128 v[192:195], v224 offset:57344
	s_waitcnt lgkmcnt(4)
	v_mfma_f32_32x32x16_bf16 v[50:65], v[206:209], v[214:217], v[50:65]
	v_mfma_f32_32x32x16_bf16 v[34:49], v[206:209], v[218:221], v[34:49]
	v_mfma_f32_32x32x16_bf16 v[18:33], v[210:213], v[214:217], v[18:33]
	v_mfma_f32_32x32x16_bf16 v[2:17], v[210:213], v[218:221], v[2:17]
	ds_read_b128 v[206:209], v123 offset:16384
	ds_read_b128 v[210:213], v123 offset:20480
	ds_read_b128 v[214:217], v225 offset:49152
	ds_read_b128 v[218:221], v225 offset:57344
	s_waitcnt lgkmcnt(4)
	v_mfma_f32_32x32x16_bf16 v[50:65], v[180:183], v[188:191], v[50:65]
	v_mfma_f32_32x32x16_bf16 v[34:49], v[180:183], v[192:195], v[34:49]
	v_mfma_f32_32x32x16_bf16 v[18:33], v[184:187], v[188:191], v[18:33]
	v_mfma_f32_32x32x16_bf16 v[2:17], v[184:187], v[192:195], v[2:17]
	s_waitcnt vmcnt(0) lgkmcnt(0)
	s_barrier
	v_mfma_f32_32x32x16_bf16 v[50:65], v[206:209], v[214:217], v[50:65]
	v_mfma_f32_32x32x16_bf16 v[34:49], v[206:209], v[218:221], v[34:49]
	v_mfma_f32_32x32x16_bf16 v[18:33], v[210:213], v[214:217], v[18:33]
	v_mfma_f32_32x32x16_bf16 v[2:17], v[210:213], v[218:221], v[2:17]
	s_branch .Lg0_join
.Lg0_pair:
	v_mov_b32_e32 v2, 0
	v_mov_b32_e32 v3, 0
	v_mov_b32_e32 v4, 0
	v_mov_b32_e32 v5, 0
	v_mov_b32_e32 v6, 0
	v_mov_b32_e32 v7, 0
	v_mov_b32_e32 v8, 0
	v_mov_b32_e32 v9, 0
	v_mov_b32_e32 v10, 0
	v_mov_b32_e32 v11, 0
	v_mov_b32_e32 v12, 0
	v_mov_b32_e32 v13, 0
	v_mov_b32_e32 v14, 0
	v_mov_b32_e32 v15, 0
	v_mov_b32_e32 v16, 0
	v_mov_b32_e32 v17, 0
	v_mov_b32_e32 v18, 0
	v_mov_b32_e32 v19, 0
	v_mov_b32_e32 v20, 0
	v_mov_b32_e32 v21, 0
	v_mov_b32_e32 v22, 0
	v_mov_b32_e32 v23, 0
	v_mov_b32_e32 v24, 0
	v_mov_b32_e32 v25, 0
	v_mov_b32_e32 v26, 0
	v_mov_b32_e32 v27, 0
	v_mov_b32_e32 v28, 0
	v_mov_b32_e32 v29, 0
	v_mov_b32_e32 v30, 0
	v_mov_b32_e32 v31, 0
	v_mov_b32_e32 v32, 0
	v_mov_b32_e32 v33, 0
	v_mov_b32_e32 v34, 0
	v_mov_b32_e32 v35, 0
	v_mov_b32_e32 v36, 0
	v_mov_b32_e32 v37, 0
	v_mov_b32_e32 v38, 0
	v_mov_b32_e32 v39, 0
	v_mov_b32_e32 v40, 0
	v_mov_b32_e32 v41, 0
	v_mov_b32_e32 v42, 0
	v_mov_b32_e32 v43, 0
	v_mov_b32_e32 v44, 0
	v_mov_b32_e32 v45, 0
	v_mov_b32_e32 v46, 0
	v_mov_b32_e32 v47, 0
	v_mov_b32_e32 v48, 0
	v_mov_b32_e32 v49, 0
	v_mov_b32_e32 v50, 0
	v_mov_b32_e32 v51, 0
	v_mov_b32_e32 v52, 0
	v_mov_b32_e32 v53, 0
	v_mov_b32_e32 v54, 0
	v_mov_b32_e32 v55, 0
	v_mov_b32_e32 v56, 0
	v_mov_b32_e32 v57, 0
	v_mov_b32_e32 v58, 0
	v_mov_b32_e32 v59, 0
	v_mov_b32_e32 v60, 0
	v_mov_b32_e32 v61, 0
	v_mov_b32_e32 v62, 0
	v_mov_b32_e32 v63, 0
	v_mov_b32_e32 v64, 0
	v_mov_b32_e32 v65, 0
	v_mov_b32_e32 v164, 0
	v_mov_b32_e32 v165, 0
	v_mov_b32_e32 v166, 0
	v_mov_b32_e32 v167, 0
	v_mov_b32_e32 v168, 0
	v_mov_b32_e32 v169, 0
	v_mov_b32_e32 v170, 0
	v_mov_b32_e32 v171, 0
	v_mov_b32_e32 v172, 0
	v_mov_b32_e32 v173, 0
	v_mov_b32_e32 v174, 0
	v_mov_b32_e32 v175, 0
	v_mov_b32_e32 v176, 0
	v_mov_b32_e32 v177, 0
	v_mov_b32_e32 v178, 0
	v_mov_b32_e32 v179, 0
	v_mov_b32_e32 v180, 0
	v_mov_b32_e32 v181, 0
	v_mov_b32_e32 v182, 0
	v_mov_b32_e32 v183, 0
	v_mov_b32_e32 v184, 0
	v_mov_b32_e32 v185, 0
	v_mov_b32_e32 v186, 0
	v_mov_b32_e32 v187, 0
	v_mov_b32_e32 v188, 0
	v_mov_b32_e32 v189, 0
	v_mov_b32_e32 v190, 0
	v_mov_b32_e32 v191, 0
	v_mov_b32_e32 v192, 0
	v_mov_b32_e32 v193, 0
	v_mov_b32_e32 v194, 0
	v_mov_b32_e32 v195, 0
	v_mov_b32_e32 v206, 0
	v_mov_b32_e32 v207, 0
	v_mov_b32_e32 v208, 0
	v_mov_b32_e32 v209, 0
	v_mov_b32_e32 v210, 0
	v_mov_b32_e32 v211, 0
	v_mov_b32_e32 v212, 0
	v_mov_b32_e32 v213, 0
	v_mov_b32_e32 v214, 0
	v_mov_b32_e32 v215, 0
	v_mov_b32_e32 v216, 0
	v_mov_b32_e32 v217, 0
	v_mov_b32_e32 v218, 0
	v_mov_b32_e32 v219, 0
	v_mov_b32_e32 v220, 0
	v_mov_b32_e32 v221, 0
	v_mov_b32_e32 v222, 0
	v_mov_b32_e32 v223, 0
	v_mov_b32_e32 v224, 0
	v_mov_b32_e32 v225, 0
	v_mov_b32_e32 v226, 0
	v_mov_b32_e32 v227, 0
	v_mov_b32_e32 v228, 0
	v_mov_b32_e32 v229, 0
	v_mov_b32_e32 v230, 0
	v_mov_b32_e32 v231, 0
	v_mov_b32_e32 v232, 0
	v_mov_b32_e32 v233, 0
	v_mov_b32_e32 v234, 0
	v_mov_b32_e32 v235, 0
	v_mov_b32_e32 v236, 0
	v_mov_b32_e32 v237, 0
	s_mov_b64 s[10:11], 0x10080
	v_lshl_add_u64 v[238:239], v[78:79], 0, s[10:11]
	s_mov_b64 s[10:11], 0x20080
	v_lshl_add_u64 v[240:241], v[78:79], 0, s[10:11]
	s_mov_b64 s[10:11], 0x30080
	v_lshl_add_u64 v[242:243], v[78:79], 0, s[10:11]
	v_lshl_add_u64 v[78:79], v[78:79], 0, s[98:99]
	s_mov_b64 s[10:11], 0x40000
	v_lshl_add_u64 v[244:245], v[70:71], 0, s[10:11]
	v_lshl_add_u64 v[246:247], v[72:73], 0, s[10:11]
	v_lshl_add_u64 v[248:249], v[74:75], 0, s[10:11]
	v_lshl_add_u64 v[250:251], v[76:77], 0, s[10:11]
	v_lshl_add_u64 v[70:71], v[70:71], 0, s[98:99]
	v_lshl_add_u64 v[72:73], v[72:73], 0, s[98:99]
	v_lshl_add_u64 v[74:75], v[74:75], 0, s[98:99]
	v_lshl_add_u64 v[76:77], v[76:77], 0, s[98:99]
	v_add_u32_e32 v124, v119, v85
	v_add_u32_e32 v124, 0x4000, v124
	v_add_u32_e32 v125, v118, v85
	v_add_u32_e32 v125, 0x4000, v125
	v_add_u32_e32 v126, v117, v85
	v_add_u32_e32 v126, 0x4000, v126
	v_add_u32_e32 v127, v116, v85
	v_add_u32_e32 v127, 0x4000, v127
	s_add_u32 m0, s22, 0xc000
	s_nop 0
	global_load_lds_dwordx4 v[244:245], off
	v_lshl_add_u64 v[244:245], v[244:245], 0, s[98:99]
	s_add_u32 m0, s22, 0xd000
	s_nop 0
	global_load_lds_dwordx4 v[246:247], off
	v_lshl_add_u64 v[246:247], v[246:247], 0, s[98:99]
	s_add_u32 m0, s22, 0xe000
	s_nop 0
	global_load_lds_dwordx4 v[248:249], off
	v_lshl_add_u64 v[248:249], v[248:249], 0, s[98:99]
	s_add_u32 m0, s22, 0xf000
	s_nop 0
	global_load_lds_dwordx4 v[250:251], off
	v_lshl_add_u64 v[250:251], v[250:251], 0, s[98:99]
	ds_read_b128 v[132:135], v120
	ds_read_b128 v[136:139], v120 offset:4096
	ds_read_b128 v[140:143], v124 offset:16384
	ds_read_b128 v[144:147], v124 offset:24576
	ds_read_b128 v[148:151], v121
	ds_read_b128 v[152:155], v121 offset:4096
	ds_read_b128 v[156:159], v125 offset:16384
	ds_read_b128 v[160:163], v125 offset:24576
	s_waitcnt lgkmcnt(4)
	v_mfma_f32_32x32x16_bf16 v[50:65], v[132:135], v[140:143], v[50:65]
	s_add_u32 m0, s22, 0x10000
	s_nop 0
	global_load_lds_dwordx4 v[70:71], off
	v_lshl_add_u64 v[70:71], v[70:71], 0, s[98:99]
	v_mfma_f32_32x32x16_bf16 v[34:49], v[132:135], v[144:147], v[34:49]
	s_add_u32 m0, s22, 0x4000
	s_nop 0
	global_load_lds_dwordx4 v[78:79], off
	v_lshl_add_u64 v[78:79], v[78:79], 0, s[98:99]
	v_mfma_f32_32x32x16_bf16 v[18:33], v[136:139], v[140:143], v[18:33]
	s_add_u32 m0, s22, 0x11000
	s_nop 0
	global_load_lds_dwordx4 v[72:73], off
	v_lshl_add_u64 v[72:73], v[72:73], 0, s[98:99]
	v_mfma_f32_32x32x16_bf16 v[2:17], v[136:139], v[144:147], v[2:17]
	ds_read_b128 v[132:135], v122
	ds_read_b128 v[136:139], v122 offset:4096
	ds_read_b128 v[140:143], v126 offset:16384
	ds_read_b128 v[144:147], v126 offset:24576
	s_waitcnt lgkmcnt(4)
	v_mfma_f32_32x32x16_bf16 v[50:65], v[148:151], v[156:159], v[50:65]
	s_add_u32 m0, s22, 0x5000
	s_nop 0
	global_load_lds_dwordx4 v[238:239], off
	v_lshl_add_u64 v[238:239], v[238:239], 0, s[98:99]
	v_mfma_f32_32x32x16_bf16 v[34:49], v[148:151], v[160:163], v[34:49]
	s_add_u32 m0, s22, 0x12000
	s_nop 0
	global_load_lds_dwordx4 v[74:75], off
	v_lshl_add_u64 v[74:75], v[74:75], 0, s[98:99]
	v_mfma_f32_32x32x16_bf16 v[18:33], v[152:155], v[156:159], v[18:33]
	s_add_u32 m0, s22, 0x6000
	s_nop 0
	global_load_lds_dwordx4 v[240:241], off
	v_lshl_add_u64 v[240:241], v[240:241], 0, s[98:99]
	v_mfma_f32_32x32x16_bf16 v[2:17], v[152:155], v[160:163], v[2:17]
	ds_read_b128 v[148:151], v123
	ds_read_b128 v[152:155], v123 offset:4096
	ds_read_b128 v[156:159], v127 offset:16384
	ds_read_b128 v[160:163], v127 offset:24576
	s_waitcnt lgkmcnt(4)
	v_mfma_f32_32x32x16_bf16 v[50:65], v[132:135], v[140:143], v[50:65]
	s_add_u32 m0, s22, 0x13000
	s_nop 0
	global_load_lds_dwordx4 v[76:77], off
	v_lshl_add_u64 v[76:77], v[76:77], 0, s[98:99]
	v_mfma_f32_32x32x16_bf16 v[34:49], v[132:135], v[144:147], v[34:49]
	s_add_u32 m0, s22, 0x7000
	s_nop 0
	global_load_lds_dwordx4 v[242:243], off
	v_lshl_add_u64 v[242:243], v[242:243], 0, s[98:99]
	v_mfma_f32_32x32x16_bf16 v[18:33], v[136:139], v[140:143], v[18:33]
	v_mfma_f32_32x32x16_bf16 v[2:17], v[136:139], v[144:147], v[2:17]
	s_waitcnt vmcnt(8) lgkmcnt(0)
	s_barrier
	ds_read_b128 v[132:135], v120
	ds_read_b128 v[136:139], v120 offset:4096
	ds_read_b128 v[140:143], v124 offset:32768
	ds_read_b128 v[144:147], v124 offset:40960
	v_mfma_f32_32x32x16_bf16 v[50:65], v[148:151], v[156:159], v[50:65]
	v_mfma_f32_32x32x16_bf16 v[34:49], v[148:151], v[160:163], v[34:49]
	v_mfma_f32_32x32x16_bf16 v[18:33], v[152:155], v[156:159], v[18:33]
	v_mfma_f32_32x32x16_bf16 v[2:17], v[152:155], v[160:163], v[2:17]
	ds_read_b128 v[148:151], v121
	ds_read_b128 v[152:155], v121 offset:4096
	ds_read_b128 v[156:159], v125 offset:32768
	ds_read_b128 v[160:163], v125 offset:40960
	s_waitcnt lgkmcnt(4)
	v_mfma_f32_32x32x16_bf16 v[164:179], v[132:135], v[140:143], v[164:179]
	s_add_u32 m0, s22, 0x8000
	s_nop 0
	global_load_lds_dwordx4 v[244:245], off
	v_lshl_add_u64 v[244:245], v[244:245], 0, s[98:99]
	v_mfma_f32_32x32x16_bf16 v[180:195], v[132:135], v[144:147], v[180:195]
	s_add_u32 m0, s22, 0x9000
	s_nop 0
	global_load_lds_dwordx4 v[246:247], off
	v_lshl_add_u64 v[246:247], v[246:247], 0, s[98:99]
	v_mfma_f32_32x32x16_bf16 v[206:221], v[136:139], v[140:143], v[206:221]
	v_mfma_f32_32x32x16_bf16 v[222:237], v[136:139], v[144:147], v[222:237]
	ds_read_b128 v[132:135], v122
	ds_read_b128 v[136:139], v122 offset:4096
	ds_read_b128 v[140:143], v126 offset:32768
	ds_read_b128 v[144:147], v126 offset:40960
	s_waitcnt lgkmcnt(4)
	v_mfma_f32_32x32x16_bf16 v[164:179], v[148:151], v[156:159], v[164:179]
	s_add_u32 m0, s22, 0xa000
	s_nop 0
	global_load_lds_dwordx4 v[248:249], off
	v_lshl_add_u64 v[248:249], v[248:249], 0, s[98:99]
	v_mfma_f32_32x32x16_bf16 v[180:195], v[148:151], v[160:163], v[180:195]
	v_mfma_f32_32x32x16_bf16 v[206:221], v[152:155], v[156:159], v[206:221]
	v_mfma_f32_32x32x16_bf16 v[222:237], v[152:155], v[160:163], v[222:237]
	ds_read_b128 v[148:151], v123
	ds_read_b128 v[152:155], v123 offset:4096
	ds_read_b128 v[156:159], v127 offset:32768
	ds_read_b128 v[160:163], v127 offset:40960
	s_waitcnt lgkmcnt(4)
	v_mfma_f32_32x32x16_bf16 v[164:179], v[132:135], v[140:143], v[164:179]
	s_add_u32 m0, s22, 0xb000
	s_nop 0
	global_load_lds_dwordx4 v[250:251], off
	v_lshl_add_u64 v[250:251], v[250:251], 0, s[98:99]
	v_mfma_f32_32x32x16_bf16 v[180:195], v[132:135], v[144:147], v[180:195]
	v_mfma_f32_32x32x16_bf16 v[206:221], v[136:139], v[140:143], v[206:221]
	v_mfma_f32_32x32x16_bf16 v[222:237], v[136:139], v[144:147], v[222:237]
	s_waitcnt vmcnt(4) lgkmcnt(0)
	s_barrier
	ds_read_b128 v[132:135], v120 offset:16384
	ds_read_b128 v[136:139], v120 offset:20480
	ds_read_b128 v[140:143], v124 offset:49152
	ds_read_b128 v[144:147], v124 offset:57344
	v_mfma_f32_32x32x16_bf16 v[164:179], v[148:151], v[156:159], v[164:179]
	v_mfma_f32_32x32x16_bf16 v[180:195], v[148:151], v[160:163], v[180:195]
	v_mfma_f32_32x32x16_bf16 v[206:221], v[152:155], v[156:159], v[206:221]
	v_mfma_f32_32x32x16_bf16 v[222:237], v[152:155], v[160:163], v[222:237]
	ds_read_b128 v[148:151], v121 offset:16384
	ds_read_b128 v[152:155], v121 offset:20480
	ds_read_b128 v[156:159], v125 offset:49152
	ds_read_b128 v[160:163], v125 offset:57344
	s_waitcnt lgkmcnt(4)
	v_mfma_f32_32x32x16_bf16 v[50:65], v[132:135], v[140:143], v[50:65]
	s_add_u32 m0, s22, 0xc000
	s_nop 0
	global_load_lds_dwordx4 v[70:71], off
	v_lshl_add_u64 v[70:71], v[70:71], 0, s[98:99]
	v_mfma_f32_32x32x16_bf16 v[34:49], v[132:135], v[144:147], v[34:49]
	s_mov_b32 m0, s22
	s_nop 0
	global_load_lds_dwordx4 v[78:79], off
	v_lshl_add_u64 v[78:79], v[78:79], 0, s[98:99]
	v_mfma_f32_32x32x16_bf16 v[18:33], v[136:139], v[140:143], v[18:33]
	s_add_u32 m0, s22, 0xd000
	s_nop 0
	global_load_lds_dwordx4 v[72:73], off
	v_lshl_add_u64 v[72:73], v[72:73], 0, s[98:99]
	v_mfma_f32_32x32x16_bf16 v[2:17], v[136:139], v[144:147], v[2:17]
	ds_read_b128 v[132:135], v122 offset:16384
	ds_read_b128 v[136:139], v122 offset:20480
	ds_read_b128 v[140:143], v126 offset:49152
	ds_read_b128 v[144:147], v126 offset:57344
	s_waitcnt lgkmcnt(4)
	v_mfma_f32_32x32x16_bf16 v[50:65], v[148:151], v[156:159], v[50:65]
	s_add_u32 m0, s22, 0x1000
	s_nop 0
	global_load_lds_dwordx4 v[238:239], off
	v_lshl_add_u64 v[238:239], v[238:239], 0, s[98:99]
	v_mfma_f32_32x32x16_bf16 v[34:49], v[148:151], v[160:163], v[34:49]
	s_add_u32 m0, s22, 0xe000
	s_nop 0
	global_load_lds_dwordx4 v[74:75], off
	v_lshl_add_u64 v[74:75], v[74:75], 0, s[98:99]
	v_mfma_f32_32x32x16_bf16 v[18:33], v[152:155], v[156:159], v[18:33]
	s_add_u32 m0, s22, 0x2000
	s_nop 0
	global_load_lds_dwordx4 v[240:241], off
	v_lshl_add_u64 v[240:241], v[240:241], 0, s[98:99]
	v_mfma_f32_32x32x16_bf16 v[2:17], v[152:155], v[160:163], v[2:17]
	ds_read_b128 v[148:151], v123 offset:16384
	ds_read_b128 v[152:155], v123 offset:20480
	ds_read_b128 v[156:159], v127 offset:49152
	ds_read_b128 v[160:163], v127 offset:57344
	s_waitcnt lgkmcnt(4)
	v_mfma_f32_32x32x16_bf16 v[50:65], v[132:135], v[140:143], v[50:65]
	s_add_u32 m0, s22, 0xf000
	s_nop 0
	global_load_lds_dwordx4 v[76:77], off
	v_lshl_add_u64 v[76:77], v[76:77], 0, s[98:99]
	v_mfma_f32_32x32x16_bf16 v[34:49], v[132:135], v[144:147], v[34:49]
	s_add_u32 m0, s22, 0x3000
	s_nop 0
	global_load_lds_dwordx4 v[242:243], off
	v_lshl_add_u64 v[242:243], v[242:243], 0, s[98:99]
	v_mfma_f32_32x32x16_bf16 v[18:33], v[136:139], v[140:143], v[18:33]
	v_mfma_f32_32x32x16_bf16 v[2:17], v[136:139], v[144:147], v[2:17]
	s_waitcnt vmcnt(8) lgkmcnt(0)
	s_barrier
	ds_read_b128 v[132:135], v120 offset:16384
	ds_read_b128 v[136:139], v120 offset:20480
	ds_read_b128 v[140:143], v124 offset:16384
	ds_read_b128 v[144:147], v124 offset:24576
	v_mfma_f32_32x32x16_bf16 v[50:65], v[148:151], v[156:159], v[50:65]
	v_mfma_f32_32x32x16_bf16 v[34:49], v[148:151], v[160:163], v[34:49]
	v_mfma_f32_32x32x16_bf16 v[18:33], v[152:155], v[156:159], v[18:33]
	v_mfma_f32_32x32x16_bf16 v[2:17], v[152:155], v[160:163], v[2:17]
	ds_read_b128 v[148:151], v121 offset:16384
	ds_read_b128 v[152:155], v121 offset:20480
	ds_read_b128 v[156:159], v125 offset:16384
	ds_read_b128 v[160:163], v125 offset:24576
	s_waitcnt lgkmcnt(4)
	v_mfma_f32_32x32x16_bf16 v[164:179], v[132:135], v[140:143], v[164:179]
	s_add_u32 m0, s22, 0x10000
	s_nop 0
	global_load_lds_dwordx4 v[244:245], off
	v_lshl_add_u64 v[244:245], v[244:245], 0, s[98:99]
	v_mfma_f32_32x32x16_bf16 v[180:195], v[132:135], v[144:147], v[180:195]
	s_add_u32 m0, s22, 0x11000
	s_nop 0
	global_load_lds_dwordx4 v[246:247], off
	v_lshl_add_u64 v[246:247], v[246:247], 0, s[98:99]
	v_mfma_f32_32x32x16_bf16 v[206:221], v[136:139], v[140:143], v[206:221]
	v_mfma_f32_32x32x16_bf16 v[222:237], v[136:139], v[144:147], v[222:237]
	ds_read_b128 v[132:135], v122 offset:16384
	ds_read_b128 v[136:139], v122 offset:20480
	ds_read_b128 v[140:143], v126 offset:16384
	ds_read_b128 v[144:147], v126 offset:24576
	s_waitcnt lgkmcnt(4)
	v_mfma_f32_32x32x16_bf16 v[164:179], v[148:151], v[156:159], v[164:179]
	s_add_u32 m0, s22, 0x12000
	s_nop 0
	global_load_lds_dwordx4 v[248:249], off
	v_lshl_add_u64 v[248:249], v[248:249], 0, s[98:99]
	v_mfma_f32_32x32x16_bf16 v[180:195], v[148:151], v[160:163], v[180:195]
	v_mfma_f32_32x32x16_bf16 v[206:221], v[152:155], v[156:159], v[206:221]
	v_mfma_f32_32x32x16_bf16 v[222:237], v[152:155], v[160:163], v[222:237]
	ds_read_b128 v[148:151], v123 offset:16384
	ds_read_b128 v[152:155], v123 offset:20480
	ds_read_b128 v[156:159], v127 offset:16384
	ds_read_b128 v[160:163], v127 offset:24576
	s_waitcnt lgkmcnt(4)
	v_mfma_f32_32x32x16_bf16 v[164:179], v[132:135], v[140:143], v[164:179]
	s_add_u32 m0, s22, 0x13000
	s_nop 0
	global_load_lds_dwordx4 v[250:251], off
	v_lshl_add_u64 v[250:251], v[250:251], 0, s[98:99]
	v_mfma_f32_32x32x16_bf16 v[180:195], v[132:135], v[144:147], v[180:195]
	v_mfma_f32_32x32x16_bf16 v[206:221], v[136:139], v[140:143], v[206:221]
	v_mfma_f32_32x32x16_bf16 v[222:237], v[136:139], v[144:147], v[222:237]
	s_waitcnt vmcnt(4) lgkmcnt(0)
	s_barrier
	ds_read_b128 v[132:135], v120
	ds_read_b128 v[136:139], v120 offset:4096
	ds_read_b128 v[140:143], v124 offset:32768
	ds_read_b128 v[144:147], v124 offset:40960
	v_mfma_f32_32x32x16_bf16 v[164:179], v[148:151], v[156:159], v[164:179]
	v_mfma_f32_32x32x16_bf16 v[180:195], v[148:151], v[160:163], v[180:195]
	v_mfma_f32_32x32x16_bf16 v[206:221], v[152:155], v[156:159], v[206:221]
	v_mfma_f32_32x32x16_bf16 v[222:237], v[152:155], v[160:163], v[222:237]
	ds_read_b128 v[148:151], v121
	ds_read_b128 v[152:155], v121 offset:4096
	ds_read_b128 v[156:159], v125 offset:32768
	ds_read_b128 v[160:163], v125 offset:40960
	s_waitcnt lgkmcnt(4)
	v_mfma_f32_32x32x16_bf16 v[50:65], v[132:135], v[140:143], v[50:65]
	s_add_u32 m0, s22, 0x8000
	s_nop 0
	global_load_lds_dwordx4 v[70:71], off
	v_lshl_add_u64 v[70:71], v[70:71], 0, s[98:99]
	v_mfma_f32_32x32x16_bf16 v[34:49], v[132:135], v[144:147], v[34:49]
	s_add_u32 m0, s22, 0x4000
	s_nop 0
	global_load_lds_dwordx4 v[78:79], off
	v_lshl_add_u64 v[78:79], v[78:79], 0, s[98:99]
	v_mfma_f32_32x32x16_bf16 v[18:33], v[136:139], v[140:143], v[18:33]
	s_add_u32 m0, s22, 0x9000
	s_nop 0
	global_load_lds_dwordx4 v[72:73], off
	v_lshl_add_u64 v[72:73], v[72:73], 0, s[98:99]
	v_mfma_f32_32x32x16_bf16 v[2:17], v[136:139], v[144:147], v[2:17]
	ds_read_b128 v[132:135], v122
	ds_read_b128 v[136:139], v122 offset:4096
	ds_read_b128 v[140:143], v126 offset:32768
	ds_read_b128 v[144:147], v126 offset:40960
	s_waitcnt lgkmcnt(4)
	v_mfma_f32_32x32x16_bf16 v[50:65], v[148:151], v[156:159], v[50:65]
	s_add_u32 m0, s22, 0x5000
	s_nop 0
	global_load_lds_dwordx4 v[238:239], off
	v_lshl_add_u64 v[238:239], v[238:239], 0, s[98:99]
	v_mfma_f32_32x32x16_bf16 v[34:49], v[148:151], v[160:163], v[34:49]
	s_add_u32 m0, s22, 0xa000
	s_nop 0
	global_load_lds_dwordx4 v[74:75], off
	v_lshl_add_u64 v[74:75], v[74:75], 0, s[98:99]
	v_mfma_f32_32x32x16_bf16 v[18:33], v[152:155], v[156:159], v[18:33]
	s_add_u32 m0, s22, 0x6000
	s_nop 0
	global_load_lds_dwordx4 v[240:241], off
	v_lshl_add_u64 v[240:241], v[240:241], 0, s[98:99]
	v_mfma_f32_32x32x16_bf16 v[2:17], v[152:155], v[160:163], v[2:17]
	ds_read_b128 v[148:151], v123
	ds_read_b128 v[152:155], v123 offset:4096
	ds_read_b128 v[156:159], v127 offset:32768
	ds_read_b128 v[160:163], v127 offset:40960
	s_waitcnt lgkmcnt(4)
	v_mfma_f32_32x32x16_bf16 v[50:65], v[132:135], v[140:143], v[50:65]
	s_add_u32 m0, s22, 0xb000
	s_nop 0
	global_load_lds_dwordx4 v[76:77], off
	v_lshl_add_u64 v[76:77], v[76:77], 0, s[98:99]
	v_mfma_f32_32x32x16_bf16 v[34:49], v[132:135], v[144:147], v[34:49]
	s_add_u32 m0, s22, 0x7000
	s_nop 0
	global_load_lds_dwordx4 v[242:243], off
	v_lshl_add_u64 v[242:243], v[242:243], 0, s[98:99]
	v_mfma_f32_32x32x16_bf16 v[18:33], v[136:139], v[140:143], v[18:33]
	v_mfma_f32_32x32x16_bf16 v[2:17], v[136:139], v[144:147], v[2:17]
	s_waitcnt vmcnt(8) lgkmcnt(0)
	s_barrier
	ds_read_b128 v[132:135], v120
	ds_read_b128 v[136:139], v120 offset:4096
	ds_read_b128 v[140:143], v124 offset:49152
	ds_read_b128 v[144:147], v124 offset:57344
	v_mfma_f32_32x32x16_bf16 v[50:65], v[148:151], v[156:159], v[50:65]
	v_mfma_f32_32x32x16_bf16 v[34:49], v[148:151], v[160:163], v[34:49]
	v_mfma_f32_32x32x16_bf16 v[18:33], v[152:155], v[156:159], v[18:33]
	v_mfma_f32_32x32x16_bf16 v[2:17], v[152:155], v[160:163], v[2:17]
	ds_read_b128 v[148:151], v121
	ds_read_b128 v[152:155], v121 offset:4096
	ds_read_b128 v[156:159], v125 offset:49152
	ds_read_b128 v[160:163], v125 offset:57344
	s_waitcnt lgkmcnt(4)
	v_mfma_f32_32x32x16_bf16 v[164:179], v[132:135], v[140:143], v[164:179]
	s_add_u32 m0, s22, 0xc000
	s_nop 0
	global_load_lds_dwordx4 v[244:245], off
	v_lshl_add_u64 v[244:245], v[244:245], 0, s[98:99]
	v_mfma_f32_32x32x16_bf16 v[180:195], v[132:135], v[144:147], v[180:195]
	s_add_u32 m0, s22, 0xd000
	s_nop 0
	global_load_lds_dwordx4 v[246:247], off
	v_lshl_add_u64 v[246:247], v[246:247], 0, s[98:99]
	v_mfma_f32_32x32x16_bf16 v[206:221], v[136:139], v[140:143], v[206:221]
	v_mfma_f32_32x32x16_bf16 v[222:237], v[136:139], v[144:147], v[222:237]
	ds_read_b128 v[132:135], v122
	ds_read_b128 v[136:139], v122 offset:4096
	ds_read_b128 v[140:143], v126 offset:49152
	ds_read_b128 v[144:147], v126 offset:57344
	s_waitcnt lgkmcnt(4)
	v_mfma_f32_32x32x16_bf16 v[164:179], v[148:151], v[156:159], v[164:179]
	s_add_u32 m0, s22, 0xe000
	s_nop 0
	global_load_lds_dwordx4 v[248:249], off
	v_lshl_add_u64 v[248:249], v[248:249], 0, s[98:99]
	v_mfma_f32_32x32x16_bf16 v[180:195], v[148:151], v[160:163], v[180:195]
	v_mfma_f32_32x32x16_bf16 v[206:221], v[152:155], v[156:159], v[206:221]
	v_mfma_f32_32x32x16_bf16 v[222:237], v[152:155], v[160:163], v[222:237]
	ds_read_b128 v[148:151], v123
	ds_read_b128 v[152:155], v123 offset:4096
	ds_read_b128 v[156:159], v127 offset:49152
	ds_read_b128 v[160:163], v127 offset:57344
	s_waitcnt lgkmcnt(4)
	v_mfma_f32_32x32x16_bf16 v[164:179], v[132:135], v[140:143], v[164:179]
	s_add_u32 m0, s22, 0xf000
	s_nop 0
	global_load_lds_dwordx4 v[250:251], off
	v_lshl_add_u64 v[250:251], v[250:251], 0, s[98:99]
	v_mfma_f32_32x32x16_bf16 v[180:195], v[132:135], v[144:147], v[180:195]
	v_mfma_f32_32x32x16_bf16 v[206:221], v[136:139], v[140:143], v[206:221]
	v_mfma_f32_32x32x16_bf16 v[222:237], v[136:139], v[144:147], v[222:237]
	s_waitcnt vmcnt(4) lgkmcnt(0)
	s_barrier
	ds_read_b128 v[132:135], v120 offset:16384
	ds_read_b128 v[136:139], v120 offset:20480
	ds_read_b128 v[140:143], v124 offset:16384
	ds_read_b128 v[144:147], v124 offset:24576
	v_mfma_f32_32x32x16_bf16 v[164:179], v[148:151], v[156:159], v[164:179]
	v_mfma_f32_32x32x16_bf16 v[180:195], v[148:151], v[160:163], v[180:195]
	v_mfma_f32_32x32x16_bf16 v[206:221], v[152:155], v[156:159], v[206:221]
	v_mfma_f32_32x32x16_bf16 v[222:237], v[152:155], v[160:163], v[222:237]
	ds_read_b128 v[148:151], v121 offset:16384
	ds_read_b128 v[152:155], v121 offset:20480
	ds_read_b128 v[156:159], v125 offset:16384
	ds_read_b128 v[160:163], v125 offset:24576
	s_waitcnt lgkmcnt(4)
	v_mfma_f32_32x32x16_bf16 v[50:65], v[132:135], v[140:143], v[50:65]
	s_add_u32 m0, s22, 0x10000
	s_nop 0
	global_load_lds_dwordx4 v[70:71], off
	v_lshl_add_u64 v[70:71], v[70:71], 0, s[98:99]
	v_mfma_f32_32x32x16_bf16 v[34:49], v[132:135], v[144:147], v[34:49]
	s_mov_b32 m0, s22
	s_nop 0
	global_load_lds_dwordx4 v[78:79], off
	v_lshl_add_u64 v[78:79], v[78:79], 0, s[98:99]
	v_mfma_f32_32x32x16_bf16 v[18:33], v[136:139], v[140:143], v[18:33]
	s_add_u32 m0, s22, 0x11000
	s_nop 0
	global_load_lds_dwordx4 v[72:73], off
	v_lshl_add_u64 v[72:73], v[72:73], 0, s[98:99]
	v_mfma_f32_32x32x16_bf16 v[2:17], v[136:139], v[144:147], v[2:17]
	ds_read_b128 v[132:135], v122 offset:16384
	ds_read_b128 v[136:139], v122 offset:20480
	ds_read_b128 v[140:143], v126 offset:16384
	ds_read_b128 v[144:147], v126 offset:24576
	s_waitcnt lgkmcnt(4)
	v_mfma_f32_32x32x16_bf16 v[50:65], v[148:151], v[156:159], v[50:65]
	s_add_u32 m0, s22, 0x1000
	s_nop 0
	global_load_lds_dwordx4 v[238:239], off
	v_lshl_add_u64 v[238:239], v[238:239], 0, s[98:99]
	v_mfma_f32_32x32x16_bf16 v[34:49], v[148:151], v[160:163], v[34:49]
	s_add_u32 m0, s22, 0x12000
	s_nop 0
	global_load_lds_dwordx4 v[74:75], off
	v_lshl_add_u64 v[74:75], v[74:75], 0, s[98:99]
	v_mfma_f32_32x32x16_bf16 v[18:33], v[152:155], v[156:159], v[18:33]
	s_add_u32 m0, s22, 0x2000
	s_nop 0
	global_load_lds_dwordx4 v[240:241], off
	v_lshl_add_u64 v[240:241], v[240:241], 0, s[98:99]
	v_mfma_f32_32x32x16_bf16 v[2:17], v[152:155], v[160:163], v[2:17]
	ds_read_b128 v[148:151], v123 offset:16384
	ds_read_b128 v[152:155], v123 offset:20480
	ds_read_b128 v[156:159], v127 offset:16384
	ds_read_b128 v[160:163], v127 offset:24576
	s_waitcnt lgkmcnt(4)
	v_mfma_f32_32x32x16_bf16 v[50:65], v[132:135], v[140:143], v[50:65]
	s_add_u32 m0, s22, 0x13000
	s_nop 0
	global_load_lds_dwordx4 v[76:77], off
	v_lshl_add_u64 v[76:77], v[76:77], 0, s[98:99]
	v_mfma_f32_32x32x16_bf16 v[34:49], v[132:135], v[144:147], v[34:49]
	s_add_u32 m0, s22, 0x3000
	s_nop 0
	global_load_lds_dwordx4 v[242:243], off
	v_lshl_add_u64 v[242:243], v[242:243], 0, s[98:99]
	v_mfma_f32_32x32x16_bf16 v[18:33], v[136:139], v[140:143], v[18:33]
	v_mfma_f32_32x32x16_bf16 v[2:17], v[136:139], v[144:147], v[2:17]
	s_waitcnt vmcnt(8) lgkmcnt(0)
	s_barrier
	ds_read_b128 v[132:135], v120 offset:16384
	ds_read_b128 v[136:139], v120 offset:20480
	ds_read_b128 v[140:143], v124 offset:32768
	ds_read_b128 v[144:147], v124 offset:40960
	v_mfma_f32_32x32x16_bf16 v[50:65], v[148:151], v[156:159], v[50:65]
	v_mfma_f32_32x32x16_bf16 v[34:49], v[148:151], v[160:163], v[34:49]
	v_mfma_f32_32x32x16_bf16 v[18:33], v[152:155], v[156:159], v[18:33]
	v_mfma_f32_32x32x16_bf16 v[2:17], v[152:155], v[160:163], v[2:17]
	ds_read_b128 v[148:151], v121 offset:16384
	ds_read_b128 v[152:155], v121 offset:20480
	ds_read_b128 v[156:159], v125 offset:32768
	ds_read_b128 v[160:163], v125 offset:40960
	s_waitcnt lgkmcnt(4)
	v_mfma_f32_32x32x16_bf16 v[164:179], v[132:135], v[140:143], v[164:179]
	s_add_u32 m0, s22, 0x8000
	s_nop 0
	global_load_lds_dwordx4 v[244:245], off
	v_lshl_add_u64 v[244:245], v[244:245], 0, s[98:99]
	v_mfma_f32_32x32x16_bf16 v[180:195], v[132:135], v[144:147], v[180:195]
	s_add_u32 m0, s22, 0x9000
	s_nop 0
	global_load_lds_dwordx4 v[246:247], off
	v_lshl_add_u64 v[246:247], v[246:247], 0, s[98:99]
	v_mfma_f32_32x32x16_bf16 v[206:221], v[136:139], v[140:143], v[206:221]
	v_mfma_f32_32x32x16_bf16 v[222:237], v[136:139], v[144:147], v[222:237]
	ds_read_b128 v[132:135], v122 offset:16384
	ds_read_b128 v[136:139], v122 offset:20480
	ds_read_b128 v[140:143], v126 offset:32768
	ds_read_b128 v[144:147], v126 offset:40960
	s_waitcnt lgkmcnt(4)
	v_mfma_f32_32x32x16_bf16 v[164:179], v[148:151], v[156:159], v[164:179]
	s_add_u32 m0, s22, 0xa000
	s_nop 0
	global_load_lds_dwordx4 v[248:249], off
	v_lshl_add_u64 v[248:249], v[248:249], 0, s[98:99]
	v_mfma_f32_32x32x16_bf16 v[180:195], v[148:151], v[160:163], v[180:195]
	v_mfma_f32_32x32x16_bf16 v[206:221], v[152:155], v[156:159], v[206:221]
	v_mfma_f32_32x32x16_bf16 v[222:237], v[152:155], v[160:163], v[222:237]
	ds_read_b128 v[148:151], v123 offset:16384
	ds_read_b128 v[152:155], v123 offset:20480
	ds_read_b128 v[156:159], v127 offset:32768
	ds_read_b128 v[160:163], v127 offset:40960
	s_waitcnt lgkmcnt(4)
	v_mfma_f32_32x32x16_bf16 v[164:179], v[132:135], v[140:143], v[164:179]
	s_add_u32 m0, s22, 0xb000
	s_nop 0
	global_load_lds_dwordx4 v[250:251], off
	v_lshl_add_u64 v[250:251], v[250:251], 0, s[98:99]
	v_mfma_f32_32x32x16_bf16 v[180:195], v[132:135], v[144:147], v[180:195]
	v_mfma_f32_32x32x16_bf16 v[206:221], v[136:139], v[140:143], v[206:221]
	v_mfma_f32_32x32x16_bf16 v[222:237], v[136:139], v[144:147], v[222:237]
	s_waitcnt vmcnt(4) lgkmcnt(0)
	s_barrier
	ds_read_b128 v[132:135], v120
	ds_read_b128 v[136:139], v120 offset:4096
	ds_read_b128 v[140:143], v124 offset:49152
	ds_read_b128 v[144:147], v124 offset:57344
	v_mfma_f32_32x32x16_bf16 v[164:179], v[148:151], v[156:159], v[164:179]
	v_mfma_f32_32x32x16_bf16 v[180:195], v[148:151], v[160:163], v[180:195]
	v_mfma_f32_32x32x16_bf16 v[206:221], v[152:155], v[156:159], v[206:221]
	v_mfma_f32_32x32x16_bf16 v[222:237], v[152:155], v[160:163], v[222:237]
	ds_read_b128 v[148:151], v121
	ds_read_b128 v[152:155], v121 offset:4096
	ds_read_b128 v[156:159], v125 offset:49152
	ds_read_b128 v[160:163], v125 offset:57344
	s_waitcnt lgkmcnt(4)
	v_mfma_f32_32x32x16_bf16 v[50:65], v[132:135], v[140:143], v[50:65]
	s_add_u32 m0, s22, 0xc000
	s_nop 0
	global_load_lds_dwordx4 v[70:71], off
	v_lshl_add_u64 v[70:71], v[70:71], 0, s[98:99]
	v_mfma_f32_32x32x16_bf16 v[34:49], v[132:135], v[144:147], v[34:49]
	s_add_u32 m0, s22, 0x4000
	s_nop 0
	global_load_lds_dwordx4 v[78:79], off
	v_lshl_add_u64 v[78:79], v[78:79], 0, s[98:99]
	v_mfma_f32_32x32x16_bf16 v[18:33], v[136:139], v[140:143], v[18:33]
	s_add_u32 m0, s22, 0xd000
	s_nop 0
	global_load_lds_dwordx4 v[72:73], off
	v_lshl_add_u64 v[72:73], v[72:73], 0, s[98:99]
	v_mfma_f32_32x32x16_bf16 v[2:17], v[136:139], v[144:147], v[2:17]
	ds_read_b128 v[132:135], v122
	ds_read_b128 v[136:139], v122 offset:4096
	ds_read_b128 v[140:143], v126 offset:49152
	ds_read_b128 v[144:147], v126 offset:57344
	s_waitcnt lgkmcnt(4)
	v_mfma_f32_32x32x16_bf16 v[50:65], v[148:151], v[156:159], v[50:65]
	s_add_u32 m0, s22, 0x5000
	s_nop 0
	global_load_lds_dwordx4 v[238:239], off
	v_lshl_add_u64 v[238:239], v[238:239], 0, s[98:99]
	v_mfma_f32_32x32x16_bf16 v[34:49], v[148:151], v[160:163], v[34:49]
	s_add_u32 m0, s22, 0xe000
	s_nop 0
	global_load_lds_dwordx4 v[74:75], off
	v_lshl_add_u64 v[74:75], v[74:75], 0, s[98:99]
	v_mfma_f32_32x32x16_bf16 v[18:33], v[152:155], v[156:159], v[18:33]
	s_add_u32 m0, s22, 0x6000
	s_nop 0
	global_load_lds_dwordx4 v[240:241], off
	v_lshl_add_u64 v[240:241], v[240:241], 0, s[98:99]
	v_mfma_f32_32x32x16_bf16 v[2:17], v[152:155], v[160:163], v[2:17]
	ds_read_b128 v[148:151], v123
	ds_read_b128 v[152:155], v123 offset:4096
	ds_read_b128 v[156:159], v127 offset:49152
	ds_read_b128 v[160:163], v127 offset:57344
	s_waitcnt lgkmcnt(4)
	v_mfma_f32_32x32x16_bf16 v[50:65], v[132:135], v[140:143], v[50:65]
	s_add_u32 m0, s22, 0xf000
	s_nop 0
	global_load_lds_dwordx4 v[76:77], off
	v_lshl_add_u64 v[76:77], v[76:77], 0, s[98:99]
	v_mfma_f32_32x32x16_bf16 v[34:49], v[132:135], v[144:147], v[34:49]
	s_add_u32 m0, s22, 0x7000
	s_nop 0
	global_load_lds_dwordx4 v[242:243], off
	v_lshl_add_u64 v[242:243], v[242:243], 0, s[98:99]
	v_mfma_f32_32x32x16_bf16 v[18:33], v[136:139], v[140:143], v[18:33]
	v_mfma_f32_32x32x16_bf16 v[2:17], v[136:139], v[144:147], v[2:17]
	s_waitcnt vmcnt(8) lgkmcnt(0)
	s_barrier
	ds_read_b128 v[132:135], v120
	ds_read_b128 v[136:139], v120 offset:4096
	ds_read_b128 v[140:143], v124 offset:16384
	ds_read_b128 v[144:147], v124 offset:24576
	v_mfma_f32_32x32x16_bf16 v[50:65], v[148:151], v[156:159], v[50:65]
	v_mfma_f32_32x32x16_bf16 v[34:49], v[148:151], v[160:163], v[34:49]
	v_mfma_f32_32x32x16_bf16 v[18:33], v[152:155], v[156:159], v[18:33]
	v_mfma_f32_32x32x16_bf16 v[2:17], v[152:155], v[160:163], v[2:17]
	ds_read_b128 v[148:151], v121
	ds_read_b128 v[152:155], v121 offset:4096
	ds_read_b128 v[156:159], v125 offset:16384
	ds_read_b128 v[160:163], v125 offset:24576
	s_waitcnt lgkmcnt(4)
	v_mfma_f32_32x32x16_bf16 v[164:179], v[132:135], v[140:143], v[164:179]
	s_add_u32 m0, s22, 0x10000
	s_nop 0
	global_load_lds_dwordx4 v[244:245], off
	v_lshl_add_u64 v[244:245], v[244:245], 0, s[98:99]
	v_mfma_f32_32x32x16_bf16 v[180:195], v[132:135], v[144:147], v[180:195]
	s_add_u32 m0, s22, 0x11000
	s_nop 0
	global_load_lds_dwordx4 v[246:247], off
	v_lshl_add_u64 v[246:247], v[246:247], 0, s[98:99]
	v_mfma_f32_32x32x16_bf16 v[206:221], v[136:139], v[140:143], v[206:221]
	v_mfma_f32_32x32x16_bf16 v[222:237], v[136:139], v[144:147], v[222:237]
	ds_read_b128 v[132:135], v122
	ds_read_b128 v[136:139], v122 offset:4096
	ds_read_b128 v[140:143], v126 offset:16384
	ds_read_b128 v[144:147], v126 offset:24576
	s_waitcnt lgkmcnt(4)
	v_mfma_f32_32x32x16_bf16 v[164:179], v[148:151], v[156:159], v[164:179]
	s_add_u32 m0, s22, 0x12000
	s_nop 0
	global_load_lds_dwordx4 v[248:249], off
	v_lshl_add_u64 v[248:249], v[248:249], 0, s[98:99]
	v_mfma_f32_32x32x16_bf16 v[180:195], v[148:151], v[160:163], v[180:195]
	v_mfma_f32_32x32x16_bf16 v[206:221], v[152:155], v[156:159], v[206:221]
	v_mfma_f32_32x32x16_bf16 v[222:237], v[152:155], v[160:163], v[222:237]
	ds_read_b128 v[148:151], v123
	ds_read_b128 v[152:155], v123 offset:4096
	ds_read_b128 v[156:159], v127 offset:16384
	ds_read_b128 v[160:163], v127 offset:24576
	s_waitcnt lgkmcnt(4)
	v_mfma_f32_32x32x16_bf16 v[164:179], v[132:135], v[140:143], v[164:179]
	s_add_u32 m0, s22, 0x13000
	s_nop 0
	global_load_lds_dwordx4 v[250:251], off
	v_lshl_add_u64 v[250:251], v[250:251], 0, s[98:99]
	v_mfma_f32_32x32x16_bf16 v[180:195], v[132:135], v[144:147], v[180:195]
	v_mfma_f32_32x32x16_bf16 v[206:221], v[136:139], v[140:143], v[206:221]
	v_mfma_f32_32x32x16_bf16 v[222:237], v[136:139], v[144:147], v[222:237]
	s_waitcnt vmcnt(4) lgkmcnt(0)
	s_barrier
	ds_read_b128 v[132:135], v120 offset:16384
	ds_read_b128 v[136:139], v120 offset:20480
	ds_read_b128 v[140:143], v124 offset:32768
	ds_read_b128 v[144:147], v124 offset:40960
	v_mfma_f32_32x32x16_bf16 v[164:179], v[148:151], v[156:159], v[164:179]
	v_mfma_f32_32x32x16_bf16 v[180:195], v[148:151], v[160:163], v[180:195]
	v_mfma_f32_32x32x16_bf16 v[206:221], v[152:155], v[156:159], v[206:221]
	v_mfma_f32_32x32x16_bf16 v[222:237], v[152:155], v[160:163], v[222:237]
	ds_read_b128 v[148:151], v121 offset:16384
	ds_read_b128 v[152:155], v121 offset:20480
	ds_read_b128 v[156:159], v125 offset:32768
	ds_read_b128 v[160:163], v125 offset:40960
	s_waitcnt lgkmcnt(4)
	v_mfma_f32_32x32x16_bf16 v[50:65], v[132:135], v[140:143], v[50:65]
	s_add_u32 m0, s22, 0x8000
	s_nop 0
	global_load_lds_dwordx4 v[70:71], off
	v_lshl_add_u64 v[70:71], v[70:71], 0, s[98:99]
	v_mfma_f32_32x32x16_bf16 v[34:49], v[132:135], v[144:147], v[34:49]
	s_mov_b32 m0, s22
	s_nop 0
	global_load_lds_dwordx4 v[78:79], off
	v_lshl_add_u64 v[78:79], v[78:79], 0, s[98:99]
	v_mfma_f32_32x32x16_bf16 v[18:33], v[136:139], v[140:143], v[18:33]
	s_add_u32 m0, s22, 0x9000
	s_nop 0
	global_load_lds_dwordx4 v[72:73], off
	v_lshl_add_u64 v[72:73], v[72:73], 0, s[98:99]
	v_mfma_f32_32x32x16_bf16 v[2:17], v[136:139], v[144:147], v[2:17]
	ds_read_b128 v[132:135], v122 offset:16384
	ds_read_b128 v[136:139], v122 offset:20480
	ds_read_b128 v[140:143], v126 offset:32768
	ds_read_b128 v[144:147], v126 offset:40960
	s_waitcnt lgkmcnt(4)
	v_mfma_f32_32x32x16_bf16 v[50:65], v[148:151], v[156:159], v[50:65]
	s_add_u32 m0, s22, 0x1000
	s_nop 0
	global_load_lds_dwordx4 v[238:239], off
	v_lshl_add_u64 v[238:239], v[238:239], 0, s[98:99]
	v_mfma_f32_32x32x16_bf16 v[34:49], v[148:151], v[160:163], v[34:49]
	s_add_u32 m0, s22, 0xa000
	s_nop 0
	global_load_lds_dwordx4 v[74:75], off
	v_lshl_add_u64 v[74:75], v[74:75], 0, s[98:99]
	v_mfma_f32_32x32x16_bf16 v[18:33], v[152:155], v[156:159], v[18:33]
	s_add_u32 m0, s22, 0x2000
	s_nop 0
	global_load_lds_dwordx4 v[240:241], off
	v_lshl_add_u64 v[240:241], v[240:241], 0, s[98:99]
	v_mfma_f32_32x32x16_bf16 v[2:17], v[152:155], v[160:163], v[2:17]
	ds_read_b128 v[148:151], v123 offset:16384
	ds_read_b128 v[152:155], v123 offset:20480
	ds_read_b128 v[156:159], v127 offset:32768
	ds_read_b128 v[160:163], v127 offset:40960
	s_waitcnt lgkmcnt(4)
	v_mfma_f32_32x32x16_bf16 v[50:65], v[132:135], v[140:143], v[50:65]
	s_add_u32 m0, s22, 0xb000
	s_nop 0
	global_load_lds_dwordx4 v[76:77], off
	v_lshl_add_u64 v[76:77], v[76:77], 0, s[98:99]
	v_mfma_f32_32x32x16_bf16 v[34:49], v[132:135], v[144:147], v[34:49]
	s_add_u32 m0, s22, 0x3000
	s_nop 0
	global_load_lds_dwordx4 v[242:243], off
	v_lshl_add_u64 v[242:243], v[242:243], 0, s[98:99]
	v_mfma_f32_32x32x16_bf16 v[18:33], v[136:139], v[140:143], v[18:33]
	v_mfma_f32_32x32x16_bf16 v[2:17], v[136:139], v[144:147], v[2:17]
	s_waitcnt vmcnt(8) lgkmcnt(0)
	s_barrier
	ds_read_b128 v[132:135], v120 offset:16384
	ds_read_b128 v[136:139], v120 offset:20480
	ds_read_b128 v[140:143], v124 offset:49152
	ds_read_b128 v[144:147], v124 offset:57344
	v_mfma_f32_32x32x16_bf16 v[50:65], v[148:151], v[156:159], v[50:65]
	v_mfma_f32_32x32x16_bf16 v[34:49], v[148:151], v[160:163], v[34:49]
	v_mfma_f32_32x32x16_bf16 v[18:33], v[152:155], v[156:159], v[18:33]
	v_mfma_f32_32x32x16_bf16 v[2:17], v[152:155], v[160:163], v[2:17]
	ds_read_b128 v[148:151], v121 offset:16384
	ds_read_b128 v[152:155], v121 offset:20480
	ds_read_b128 v[156:159], v125 offset:49152
	ds_read_b128 v[160:163], v125 offset:57344
	s_waitcnt lgkmcnt(4)
	v_mfma_f32_32x32x16_bf16 v[164:179], v[132:135], v[140:143], v[164:179]
	s_add_u32 m0, s22, 0xc000
	s_nop 0
	global_load_lds_dwordx4 v[244:245], off
	v_lshl_add_u64 v[244:245], v[244:245], 0, s[98:99]
	v_mfma_f32_32x32x16_bf16 v[180:195], v[132:135], v[144:147], v[180:195]
	s_add_u32 m0, s22, 0xd000
	s_nop 0
	global_load_lds_dwordx4 v[246:247], off
	v_lshl_add_u64 v[246:247], v[246:247], 0, s[98:99]
	v_mfma_f32_32x32x16_bf16 v[206:221], v[136:139], v[140:143], v[206:221]
	v_mfma_f32_32x32x16_bf16 v[222:237], v[136:139], v[144:147], v[222:237]
	ds_read_b128 v[132:135], v122 offset:16384
	ds_read_b128 v[136:139], v122 offset:20480
	ds_read_b128 v[140:143], v126 offset:49152
	ds_read_b128 v[144:147], v126 offset:57344
	s_waitcnt lgkmcnt(4)
	v_mfma_f32_32x32x16_bf16 v[164:179], v[148:151], v[156:159], v[164:179]
	s_add_u32 m0, s22, 0xe000
	s_nop 0
	global_load_lds_dwordx4 v[248:249], off
	v_lshl_add_u64 v[248:249], v[248:249], 0, s[98:99]
	v_mfma_f32_32x32x16_bf16 v[180:195], v[148:151], v[160:163], v[180:195]
	v_mfma_f32_32x32x16_bf16 v[206:221], v[152:155], v[156:159], v[206:221]
	v_mfma_f32_32x32x16_bf16 v[222:237], v[152:155], v[160:163], v[222:237]
	ds_read_b128 v[148:151], v123 offset:16384
	ds_read_b128 v[152:155], v123 offset:20480
	ds_read_b128 v[156:159], v127 offset:49152
	ds_read_b128 v[160:163], v127 offset:57344
	s_waitcnt lgkmcnt(4)
	v_mfma_f32_32x32x16_bf16 v[164:179], v[132:135], v[140:143], v[164:179]
	s_add_u32 m0, s22, 0xf000
	s_nop 0
	global_load_lds_dwordx4 v[250:251], off
	v_lshl_add_u64 v[250:251], v[250:251], 0, s[98:99]
	v_mfma_f32_32x32x16_bf16 v[180:195], v[132:135], v[144:147], v[180:195]
	v_mfma_f32_32x32x16_bf16 v[206:221], v[136:139], v[140:143], v[206:221]
	v_mfma_f32_32x32x16_bf16 v[222:237], v[136:139], v[144:147], v[222:237]
	s_waitcnt vmcnt(4) lgkmcnt(0)
	s_barrier
	ds_read_b128 v[132:135], v120
	ds_read_b128 v[136:139], v120 offset:4096
	ds_read_b128 v[140:143], v124 offset:16384
	ds_read_b128 v[144:147], v124 offset:24576
	v_mfma_f32_32x32x16_bf16 v[164:179], v[148:151], v[156:159], v[164:179]
	v_mfma_f32_32x32x16_bf16 v[180:195], v[148:151], v[160:163], v[180:195]
	v_mfma_f32_32x32x16_bf16 v[206:221], v[152:155], v[156:159], v[206:221]
	v_mfma_f32_32x32x16_bf16 v[222:237], v[152:155], v[160:163], v[222:237]
	ds_read_b128 v[148:151], v121
	ds_read_b128 v[152:155], v121 offset:4096
	ds_read_b128 v[156:159], v125 offset:16384
	ds_read_b128 v[160:163], v125 offset:24576
	s_waitcnt lgkmcnt(4)
	v_mfma_f32_32x32x16_bf16 v[50:65], v[132:135], v[140:143], v[50:65]
	s_add_u32 m0, s22, 0x10000
	s_nop 0
	global_load_lds_dwordx4 v[70:71], off
	v_lshl_add_u64 v[70:71], v[70:71], 0, s[98:99]
	v_mfma_f32_32x32x16_bf16 v[34:49], v[132:135], v[144:147], v[34:49]
	s_add_u32 m0, s22, 0x4000
	s_nop 0
	global_load_lds_dwordx4 v[78:79], off
	v_lshl_add_u64 v[78:79], v[78:79], 0, s[98:99]
	v_mfma_f32_32x32x16_bf16 v[18:33], v[136:139], v[140:143], v[18:33]
	s_add_u32 m0, s22, 0x11000
	s_nop 0
	global_load_lds_dwordx4 v[72:73], off
	v_lshl_add_u64 v[72:73], v[72:73], 0, s[98:99]
	v_mfma_f32_32x32x16_bf16 v[2:17], v[136:139], v[144:147], v[2:17]
	ds_read_b128 v[132:135], v122
	ds_read_b128 v[136:139], v122 offset:4096
	ds_read_b128 v[140:143], v126 offset:16384
	ds_read_b128 v[144:147], v126 offset:24576
	s_waitcnt lgkmcnt(4)
	v_mfma_f32_32x32x16_bf16 v[50:65], v[148:151], v[156:159], v[50:65]
	s_add_u32 m0, s22, 0x5000
	s_nop 0
	global_load_lds_dwordx4 v[238:239], off
	v_lshl_add_u64 v[238:239], v[238:239], 0, s[98:99]
	v_mfma_f32_32x32x16_bf16 v[34:49], v[148:151], v[160:163], v[34:49]
	s_add_u32 m0, s22, 0x12000
	s_nop 0
	global_load_lds_dwordx4 v[74:75], off
	v_lshl_add_u64 v[74:75], v[74:75], 0, s[98:99]
	v_mfma_f32_32x32x16_bf16 v[18:33], v[152:155], v[156:159], v[18:33]
	s_add_u32 m0, s22, 0x6000
	s_nop 0
	global_load_lds_dwordx4 v[240:241], off
	v_lshl_add_u64 v[240:241], v[240:241], 0, s[98:99]
	v_mfma_f32_32x32x16_bf16 v[2:17], v[152:155], v[160:163], v[2:17]
	ds_read_b128 v[148:151], v123
	ds_read_b128 v[152:155], v123 offset:4096
	ds_read_b128 v[156:159], v127 offset:16384
	ds_read_b128 v[160:163], v127 offset:24576
	s_waitcnt lgkmcnt(4)
	v_mfma_f32_32x32x16_bf16 v[50:65], v[132:135], v[140:143], v[50:65]
	s_add_u32 m0, s22, 0x13000
	s_nop 0
	global_load_lds_dwordx4 v[76:77], off
	v_lshl_add_u64 v[76:77], v[76:77], 0, s[98:99]
	v_mfma_f32_32x32x16_bf16 v[34:49], v[132:135], v[144:147], v[34:49]
	s_add_u32 m0, s22, 0x7000
	s_nop 0
	global_load_lds_dwordx4 v[242:243], off
	v_lshl_add_u64 v[242:243], v[242:243], 0, s[98:99]
	v_mfma_f32_32x32x16_bf16 v[18:33], v[136:139], v[140:143], v[18:33]
	v_mfma_f32_32x32x16_bf16 v[2:17], v[136:139], v[144:147], v[2:17]
	s_waitcnt vmcnt(8) lgkmcnt(0)
	s_barrier
	ds_read_b128 v[132:135], v120
	ds_read_b128 v[136:139], v120 offset:4096
	ds_read_b128 v[140:143], v124 offset:32768
	ds_read_b128 v[144:147], v124 offset:40960
	v_mfma_f32_32x32x16_bf16 v[50:65], v[148:151], v[156:159], v[50:65]
	v_mfma_f32_32x32x16_bf16 v[34:49], v[148:151], v[160:163], v[34:49]
	v_mfma_f32_32x32x16_bf16 v[18:33], v[152:155], v[156:159], v[18:33]
	v_mfma_f32_32x32x16_bf16 v[2:17], v[152:155], v[160:163], v[2:17]
	ds_read_b128 v[148:151], v121
	ds_read_b128 v[152:155], v121 offset:4096
	ds_read_b128 v[156:159], v125 offset:32768
	ds_read_b128 v[160:163], v125 offset:40960
	s_waitcnt lgkmcnt(4)
	v_mfma_f32_32x32x16_bf16 v[164:179], v[132:135], v[140:143], v[164:179]
	s_add_u32 m0, s22, 0x8000
	s_nop 0
	global_load_lds_dwordx4 v[244:245], off
	v_lshl_add_u64 v[244:245], v[244:245], 0, s[98:99]
	v_mfma_f32_32x32x16_bf16 v[180:195], v[132:135], v[144:147], v[180:195]
	s_add_u32 m0, s22, 0x9000
	s_nop 0
	global_load_lds_dwordx4 v[246:247], off
	v_lshl_add_u64 v[246:247], v[246:247], 0, s[98:99]
	v_mfma_f32_32x32x16_bf16 v[206:221], v[136:139], v[140:143], v[206:221]
	v_mfma_f32_32x32x16_bf16 v[222:237], v[136:139], v[144:147], v[222:237]
	ds_read_b128 v[132:135], v122
	ds_read_b128 v[136:139], v122 offset:4096
	ds_read_b128 v[140:143], v126 offset:32768
	ds_read_b128 v[144:147], v126 offset:40960
	s_waitcnt lgkmcnt(4)
	v_mfma_f32_32x32x16_bf16 v[164:179], v[148:151], v[156:159], v[164:179]
	s_add_u32 m0, s22, 0xa000
	s_nop 0
	global_load_lds_dwordx4 v[248:249], off
	v_lshl_add_u64 v[248:249], v[248:249], 0, s[98:99]
	v_mfma_f32_32x32x16_bf16 v[180:195], v[148:151], v[160:163], v[180:195]
	v_mfma_f32_32x32x16_bf16 v[206:221], v[152:155], v[156:159], v[206:221]
	v_mfma_f32_32x32x16_bf16 v[222:237], v[152:155], v[160:163], v[222:237]
	ds_read_b128 v[148:151], v123
	ds_read_b128 v[152:155], v123 offset:4096
	ds_read_b128 v[156:159], v127 offset:32768
	ds_read_b128 v[160:163], v127 offset:40960
	s_waitcnt lgkmcnt(4)
	v_mfma_f32_32x32x16_bf16 v[164:179], v[132:135], v[140:143], v[164:179]
	s_add_u32 m0, s22, 0xb000
	s_nop 0
	global_load_lds_dwordx4 v[250:251], off
	v_lshl_add_u64 v[250:251], v[250:251], 0, s[98:99]
	v_mfma_f32_32x32x16_bf16 v[180:195], v[132:135], v[144:147], v[180:195]
	v_mfma_f32_32x32x16_bf16 v[206:221], v[136:139], v[140:143], v[206:221]
	v_mfma_f32_32x32x16_bf16 v[222:237], v[136:139], v[144:147], v[222:237]
	s_waitcnt vmcnt(4) lgkmcnt(0)
	s_barrier
	ds_read_b128 v[132:135], v120 offset:16384
	ds_read_b128 v[136:139], v120 offset:20480
	ds_read_b128 v[140:143], v124 offset:49152
	ds_read_b128 v[144:147], v124 offset:57344
	v_mfma_f32_32x32x16_bf16 v[164:179], v[148:151], v[156:159], v[164:179]
	v_mfma_f32_32x32x16_bf16 v[180:195], v[148:151], v[160:163], v[180:195]
	v_mfma_f32_32x32x16_bf16 v[206:221], v[152:155], v[156:159], v[206:221]
	v_mfma_f32_32x32x16_bf16 v[222:237], v[152:155], v[160:163], v[222:237]
	ds_read_b128 v[148:151], v121 offset:16384
	ds_read_b128 v[152:155], v121 offset:20480
	ds_read_b128 v[156:159], v125 offset:49152
	ds_read_b128 v[160:163], v125 offset:57344
	s_waitcnt lgkmcnt(4)
	v_mfma_f32_32x32x16_bf16 v[50:65], v[132:135], v[140:143], v[50:65]
	s_add_u32 m0, s22, 0xc000
	s_nop 0
	global_load_lds_dwordx4 v[70:71], off
	v_lshl_add_u64 v[70:71], v[70:71], 0, s[98:99]
	v_mfma_f32_32x32x16_bf16 v[34:49], v[132:135], v[144:147], v[34:49]
	s_mov_b32 m0, s22
	s_nop 0
	global_load_lds_dwordx4 v[78:79], off
	v_lshl_add_u64 v[78:79], v[78:79], 0, s[98:99]
	v_mfma_f32_32x32x16_bf16 v[18:33], v[136:139], v[140:143], v[18:33]
	s_add_u32 m0, s22, 0xd000
	s_nop 0
	global_load_lds_dwordx4 v[72:73], off
	v_lshl_add_u64 v[72:73], v[72:73], 0, s[98:99]
	v_mfma_f32_32x32x16_bf16 v[2:17], v[136:139], v[144:147], v[2:17]
	ds_read_b128 v[132:135], v122 offset:16384
	ds_read_b128 v[136:139], v122 offset:20480
	ds_read_b128 v[140:143], v126 offset:49152
	ds_read_b128 v[144:147], v126 offset:57344
	s_waitcnt lgkmcnt(4)
	v_mfma_f32_32x32x16_bf16 v[50:65], v[148:151], v[156:159], v[50:65]
	s_add_u32 m0, s22, 0x1000
	s_nop 0
	global_load_lds_dwordx4 v[238:239], off
	v_lshl_add_u64 v[238:239], v[238:239], 0, s[98:99]
	v_mfma_f32_32x32x16_bf16 v[34:49], v[148:151], v[160:163], v[34:49]
	s_add_u32 m0, s22, 0xe000
	s_nop 0
	global_load_lds_dwordx4 v[74:75], off
	v_lshl_add_u64 v[74:75], v[74:75], 0, s[98:99]
	v_mfma_f32_32x32x16_bf16 v[18:33], v[152:155], v[156:159], v[18:33]
	s_add_u32 m0, s22, 0x2000
	s_nop 0
	global_load_lds_dwordx4 v[240:241], off
	v_lshl_add_u64 v[240:241], v[240:241], 0, s[98:99]
	v_mfma_f32_32x32x16_bf16 v[2:17], v[152:155], v[160:163], v[2:17]
	ds_read_b128 v[148:151], v123 offset:16384
	ds_read_b128 v[152:155], v123 offset:20480
	ds_read_b128 v[156:159], v127 offset:49152
	ds_read_b128 v[160:163], v127 offset:57344
	s_waitcnt lgkmcnt(4)
	v_mfma_f32_32x32x16_bf16 v[50:65], v[132:135], v[140:143], v[50:65]
	s_add_u32 m0, s22, 0xf000
	s_nop 0
	global_load_lds_dwordx4 v[76:77], off
	v_lshl_add_u64 v[76:77], v[76:77], 0, s[98:99]
	v_mfma_f32_32x32x16_bf16 v[34:49], v[132:135], v[144:147], v[34:49]
	s_add_u32 m0, s22, 0x3000
	s_nop 0
	global_load_lds_dwordx4 v[242:243], off
	v_lshl_add_u64 v[242:243], v[242:243], 0, s[98:99]
	v_mfma_f32_32x32x16_bf16 v[18:33], v[136:139], v[140:143], v[18:33]
	v_mfma_f32_32x32x16_bf16 v[2:17], v[136:139], v[144:147], v[2:17]
	s_waitcnt vmcnt(8) lgkmcnt(0)
	s_barrier
	ds_read_b128 v[132:135], v120 offset:16384
	ds_read_b128 v[136:139], v120 offset:20480
	ds_read_b128 v[140:143], v124 offset:16384
	ds_read_b128 v[144:147], v124 offset:24576
	v_mfma_f32_32x32x16_bf16 v[50:65], v[148:151], v[156:159], v[50:65]
	v_mfma_f32_32x32x16_bf16 v[34:49], v[148:151], v[160:163], v[34:49]
	v_mfma_f32_32x32x16_bf16 v[18:33], v[152:155], v[156:159], v[18:33]
	v_mfma_f32_32x32x16_bf16 v[2:17], v[152:155], v[160:163], v[2:17]
	ds_read_b128 v[148:151], v121 offset:16384
	ds_read_b128 v[152:155], v121 offset:20480
	ds_read_b128 v[156:159], v125 offset:16384
	ds_read_b128 v[160:163], v125 offset:24576
	s_waitcnt lgkmcnt(4)
	v_mfma_f32_32x32x16_bf16 v[164:179], v[132:135], v[140:143], v[164:179]
	s_add_u32 m0, s22, 0x10000
	s_nop 0
	global_load_lds_dwordx4 v[244:245], off
	v_lshl_add_u64 v[244:245], v[244:245], 0, s[98:99]
	v_mfma_f32_32x32x16_bf16 v[180:195], v[132:135], v[144:147], v[180:195]
	s_add_u32 m0, s22, 0x11000
	s_nop 0
	global_load_lds_dwordx4 v[246:247], off
	v_lshl_add_u64 v[246:247], v[246:247], 0, s[98:99]
	v_mfma_f32_32x32x16_bf16 v[206:221], v[136:139], v[140:143], v[206:221]
	v_mfma_f32_32x32x16_bf16 v[222:237], v[136:139], v[144:147], v[222:237]
	ds_read_b128 v[132:135], v122 offset:16384
	ds_read_b128 v[136:139], v122 offset:20480
	ds_read_b128 v[140:143], v126 offset:16384
	ds_read_b128 v[144:147], v126 offset:24576
	s_waitcnt lgkmcnt(4)
	v_mfma_f32_32x32x16_bf16 v[164:179], v[148:151], v[156:159], v[164:179]
	s_add_u32 m0, s22, 0x12000
	s_nop 0
	global_load_lds_dwordx4 v[248:249], off
	v_lshl_add_u64 v[248:249], v[248:249], 0, s[98:99]
	v_mfma_f32_32x32x16_bf16 v[180:195], v[148:151], v[160:163], v[180:195]
	v_mfma_f32_32x32x16_bf16 v[206:221], v[152:155], v[156:159], v[206:221]
	v_mfma_f32_32x32x16_bf16 v[222:237], v[152:155], v[160:163], v[222:237]
	ds_read_b128 v[148:151], v123 offset:16384
	ds_read_b128 v[152:155], v123 offset:20480
	ds_read_b128 v[156:159], v127 offset:16384
	ds_read_b128 v[160:163], v127 offset:24576
	s_waitcnt lgkmcnt(4)
	v_mfma_f32_32x32x16_bf16 v[164:179], v[132:135], v[140:143], v[164:179]
	s_add_u32 m0, s22, 0x13000
	s_nop 0
	global_load_lds_dwordx4 v[250:251], off
	v_lshl_add_u64 v[250:251], v[250:251], 0, s[98:99]
	v_mfma_f32_32x32x16_bf16 v[180:195], v[132:135], v[144:147], v[180:195]
	v_mfma_f32_32x32x16_bf16 v[206:221], v[136:139], v[140:143], v[206:221]
	v_mfma_f32_32x32x16_bf16 v[222:237], v[136:139], v[144:147], v[222:237]
	s_waitcnt vmcnt(4) lgkmcnt(0)
	s_barrier
	ds_read_b128 v[132:135], v120
	ds_read_b128 v[136:139], v120 offset:4096
	ds_read_b128 v[140:143], v124 offset:32768
	ds_read_b128 v[144:147], v124 offset:40960
	v_mfma_f32_32x32x16_bf16 v[164:179], v[148:151], v[156:159], v[164:179]
	v_mfma_f32_32x32x16_bf16 v[180:195], v[148:151], v[160:163], v[180:195]
	v_mfma_f32_32x32x16_bf16 v[206:221], v[152:155], v[156:159], v[206:221]
	v_mfma_f32_32x32x16_bf16 v[222:237], v[152:155], v[160:163], v[222:237]
	ds_read_b128 v[148:151], v121
	ds_read_b128 v[152:155], v121 offset:4096
	ds_read_b128 v[156:159], v125 offset:32768
	ds_read_b128 v[160:163], v125 offset:40960
	s_waitcnt lgkmcnt(4)
	v_mfma_f32_32x32x16_bf16 v[50:65], v[132:135], v[140:143], v[50:65]
	s_add_u32 m0, s22, 0x8000
	s_nop 0
	global_load_lds_dwordx4 v[70:71], off
	v_lshl_add_u64 v[70:71], v[70:71], 0, s[98:99]
	v_mfma_f32_32x32x16_bf16 v[34:49], v[132:135], v[144:147], v[34:49]
	s_add_u32 m0, s22, 0x4000
	s_nop 0
	global_load_lds_dwordx4 v[78:79], off
	v_lshl_add_u64 v[78:79], v[78:79], 0, s[98:99]
	v_mfma_f32_32x32x16_bf16 v[18:33], v[136:139], v[140:143], v[18:33]
	s_add_u32 m0, s22, 0x9000
	s_nop 0
	global_load_lds_dwordx4 v[72:73], off
	v_lshl_add_u64 v[72:73], v[72:73], 0, s[98:99]
	v_mfma_f32_32x32x16_bf16 v[2:17], v[136:139], v[144:147], v[2:17]
	ds_read_b128 v[132:135], v122
	ds_read_b128 v[136:139], v122 offset:4096
	ds_read_b128 v[140:143], v126 offset:32768
	ds_read_b128 v[144:147], v126 offset:40960
	s_waitcnt lgkmcnt(4)
	v_mfma_f32_32x32x16_bf16 v[50:65], v[148:151], v[156:159], v[50:65]
	s_add_u32 m0, s22, 0x5000
	s_nop 0
	global_load_lds_dwordx4 v[238:239], off
	v_lshl_add_u64 v[238:239], v[238:239], 0, s[98:99]
	v_mfma_f32_32x32x16_bf16 v[34:49], v[148:151], v[160:163], v[34:49]
	s_add_u32 m0, s22, 0xa000
	s_nop 0
	global_load_lds_dwordx4 v[74:75], off
	v_lshl_add_u64 v[74:75], v[74:75], 0, s[98:99]
	v_mfma_f32_32x32x16_bf16 v[18:33], v[152:155], v[156:159], v[18:33]
	s_add_u32 m0, s22, 0x6000
	s_nop 0
	global_load_lds_dwordx4 v[240:241], off
	v_lshl_add_u64 v[240:241], v[240:241], 0, s[98:99]
	v_mfma_f32_32x32x16_bf16 v[2:17], v[152:155], v[160:163], v[2:17]
	ds_read_b128 v[148:151], v123
	ds_read_b128 v[152:155], v123 offset:4096
	ds_read_b128 v[156:159], v127 offset:32768
	ds_read_b128 v[160:163], v127 offset:40960
	s_waitcnt lgkmcnt(4)
	v_mfma_f32_32x32x16_bf16 v[50:65], v[132:135], v[140:143], v[50:65]
	s_add_u32 m0, s22, 0xb000
	s_nop 0
	global_load_lds_dwordx4 v[76:77], off
	v_lshl_add_u64 v[76:77], v[76:77], 0, s[98:99]
	v_mfma_f32_32x32x16_bf16 v[34:49], v[132:135], v[144:147], v[34:49]
	s_add_u32 m0, s22, 0x7000
	s_nop 0
	global_load_lds_dwordx4 v[242:243], off
	v_lshl_add_u64 v[242:243], v[242:243], 0, s[98:99]
	v_mfma_f32_32x32x16_bf16 v[18:33], v[136:139], v[140:143], v[18:33]
	v_mfma_f32_32x32x16_bf16 v[2:17], v[136:139], v[144:147], v[2:17]
	s_waitcnt vmcnt(8) lgkmcnt(0)
	s_barrier
	ds_read_b128 v[132:135], v120
	ds_read_b128 v[136:139], v120 offset:4096
	ds_read_b128 v[140:143], v124 offset:49152
	ds_read_b128 v[144:147], v124 offset:57344
	v_mfma_f32_32x32x16_bf16 v[50:65], v[148:151], v[156:159], v[50:65]
	v_mfma_f32_32x32x16_bf16 v[34:49], v[148:151], v[160:163], v[34:49]
	v_mfma_f32_32x32x16_bf16 v[18:33], v[152:155], v[156:159], v[18:33]
	v_mfma_f32_32x32x16_bf16 v[2:17], v[152:155], v[160:163], v[2:17]
	ds_read_b128 v[148:151], v121
	ds_read_b128 v[152:155], v121 offset:4096
	ds_read_b128 v[156:159], v125 offset:49152
	ds_read_b128 v[160:163], v125 offset:57344
	s_waitcnt lgkmcnt(4)
	v_mfma_f32_32x32x16_bf16 v[164:179], v[132:135], v[140:143], v[164:179]
	s_add_u32 m0, s22, 0xc000
	s_nop 0
	global_load_lds_dwordx4 v[244:245], off
	v_lshl_add_u64 v[244:245], v[244:245], 0, s[98:99]
	v_mfma_f32_32x32x16_bf16 v[180:195], v[132:135], v[144:147], v[180:195]
	s_add_u32 m0, s22, 0xd000
	s_nop 0
	global_load_lds_dwordx4 v[246:247], off
	v_lshl_add_u64 v[246:247], v[246:247], 0, s[98:99]
	v_mfma_f32_32x32x16_bf16 v[206:221], v[136:139], v[140:143], v[206:221]
	v_mfma_f32_32x32x16_bf16 v[222:237], v[136:139], v[144:147], v[222:237]
	ds_read_b128 v[132:135], v122
	ds_read_b128 v[136:139], v122 offset:4096
	ds_read_b128 v[140:143], v126 offset:49152
	ds_read_b128 v[144:147], v126 offset:57344
	s_waitcnt lgkmcnt(4)
	v_mfma_f32_32x32x16_bf16 v[164:179], v[148:151], v[156:159], v[164:179]
	s_add_u32 m0, s22, 0xe000
	s_nop 0
	global_load_lds_dwordx4 v[248:249], off
	v_lshl_add_u64 v[248:249], v[248:249], 0, s[98:99]
	v_mfma_f32_32x32x16_bf16 v[180:195], v[148:151], v[160:163], v[180:195]
	v_mfma_f32_32x32x16_bf16 v[206:221], v[152:155], v[156:159], v[206:221]
	v_mfma_f32_32x32x16_bf16 v[222:237], v[152:155], v[160:163], v[222:237]
	ds_read_b128 v[148:151], v123
	ds_read_b128 v[152:155], v123 offset:4096
	ds_read_b128 v[156:159], v127 offset:49152
	ds_read_b128 v[160:163], v127 offset:57344
	s_waitcnt lgkmcnt(4)
	v_mfma_f32_32x32x16_bf16 v[164:179], v[132:135], v[140:143], v[164:179]
	s_add_u32 m0, s22, 0xf000
	s_nop 0
	global_load_lds_dwordx4 v[250:251], off
	v_lshl_add_u64 v[250:251], v[250:251], 0, s[98:99]
	v_mfma_f32_32x32x16_bf16 v[180:195], v[132:135], v[144:147], v[180:195]
	v_mfma_f32_32x32x16_bf16 v[206:221], v[136:139], v[140:143], v[206:221]
	v_mfma_f32_32x32x16_bf16 v[222:237], v[136:139], v[144:147], v[222:237]
	s_waitcnt vmcnt(4) lgkmcnt(0)
	s_barrier
	ds_read_b128 v[132:135], v120 offset:16384
	ds_read_b128 v[136:139], v120 offset:20480
	ds_read_b128 v[140:143], v124 offset:16384
	ds_read_b128 v[144:147], v124 offset:24576
	v_mfma_f32_32x32x16_bf16 v[164:179], v[148:151], v[156:159], v[164:179]
	v_mfma_f32_32x32x16_bf16 v[180:195], v[148:151], v[160:163], v[180:195]
	v_mfma_f32_32x32x16_bf16 v[206:221], v[152:155], v[156:159], v[206:221]
	v_mfma_f32_32x32x16_bf16 v[222:237], v[152:155], v[160:163], v[222:237]
	ds_read_b128 v[148:151], v121 offset:16384
	ds_read_b128 v[152:155], v121 offset:20480
	ds_read_b128 v[156:159], v125 offset:16384
	ds_read_b128 v[160:163], v125 offset:24576
	s_waitcnt lgkmcnt(4)
	v_mfma_f32_32x32x16_bf16 v[50:65], v[132:135], v[140:143], v[50:65]
	s_add_u32 m0, s22, 0x10000
	s_nop 0
	global_load_lds_dwordx4 v[70:71], off
	v_lshl_add_u64 v[70:71], v[70:71], 0, s[98:99]
	v_mfma_f32_32x32x16_bf16 v[34:49], v[132:135], v[144:147], v[34:49]
	s_mov_b32 m0, s22
	s_nop 0
	global_load_lds_dwordx4 v[78:79], off
	v_lshl_add_u64 v[78:79], v[78:79], 0, s[98:99]
	v_mfma_f32_32x32x16_bf16 v[18:33], v[136:139], v[140:143], v[18:33]
	s_add_u32 m0, s22, 0x11000
	s_nop 0
	global_load_lds_dwordx4 v[72:73], off
	v_lshl_add_u64 v[72:73], v[72:73], 0, s[98:99]
	v_mfma_f32_32x32x16_bf16 v[2:17], v[136:139], v[144:147], v[2:17]
	ds_read_b128 v[132:135], v122 offset:16384
	ds_read_b128 v[136:139], v122 offset:20480
	ds_read_b128 v[140:143], v126 offset:16384
	ds_read_b128 v[144:147], v126 offset:24576
	s_waitcnt lgkmcnt(4)
	v_mfma_f32_32x32x16_bf16 v[50:65], v[148:151], v[156:159], v[50:65]
	s_add_u32 m0, s22, 0x1000
	s_nop 0
	global_load_lds_dwordx4 v[238:239], off
	v_lshl_add_u64 v[238:239], v[238:239], 0, s[98:99]
	v_mfma_f32_32x32x16_bf16 v[34:49], v[148:151], v[160:163], v[34:49]
	s_add_u32 m0, s22, 0x12000
	s_nop 0
	global_load_lds_dwordx4 v[74:75], off
	v_lshl_add_u64 v[74:75], v[74:75], 0, s[98:99]
	v_mfma_f32_32x32x16_bf16 v[18:33], v[152:155], v[156:159], v[18:33]
	s_add_u32 m0, s22, 0x2000
	s_nop 0
	global_load_lds_dwordx4 v[240:241], off
	v_lshl_add_u64 v[240:241], v[240:241], 0, s[98:99]
	v_mfma_f32_32x32x16_bf16 v[2:17], v[152:155], v[160:163], v[2:17]
	ds_read_b128 v[148:151], v123 offset:16384
	ds_read_b128 v[152:155], v123 offset:20480
	ds_read_b128 v[156:159], v127 offset:16384
	ds_read_b128 v[160:163], v127 offset:24576
	s_waitcnt lgkmcnt(4)
	v_mfma_f32_32x32x16_bf16 v[50:65], v[132:135], v[140:143], v[50:65]
	s_add_u32 m0, s22, 0x13000
	s_nop 0
	global_load_lds_dwordx4 v[76:77], off
	v_lshl_add_u64 v[76:77], v[76:77], 0, s[98:99]
	v_mfma_f32_32x32x16_bf16 v[34:49], v[132:135], v[144:147], v[34:49]
	s_add_u32 m0, s22, 0x3000
	s_nop 0
	global_load_lds_dwordx4 v[242:243], off
	v_lshl_add_u64 v[242:243], v[242:243], 0, s[98:99]
	v_mfma_f32_32x32x16_bf16 v[18:33], v[136:139], v[140:143], v[18:33]
	v_mfma_f32_32x32x16_bf16 v[2:17], v[136:139], v[144:147], v[2:17]
	s_waitcnt vmcnt(8) lgkmcnt(0)
	s_barrier
	ds_read_b128 v[132:135], v120 offset:16384
	ds_read_b128 v[136:139], v120 offset:20480
	ds_read_b128 v[140:143], v124 offset:32768
	ds_read_b128 v[144:147], v124 offset:40960
	v_mfma_f32_32x32x16_bf16 v[50:65], v[148:151], v[156:159], v[50:65]
	v_mfma_f32_32x32x16_bf16 v[34:49], v[148:151], v[160:163], v[34:49]
	v_mfma_f32_32x32x16_bf16 v[18:33], v[152:155], v[156:159], v[18:33]
	v_mfma_f32_32x32x16_bf16 v[2:17], v[152:155], v[160:163], v[2:17]
	ds_read_b128 v[148:151], v121 offset:16384
	ds_read_b128 v[152:155], v121 offset:20480
	ds_read_b128 v[156:159], v125 offset:32768
	ds_read_b128 v[160:163], v125 offset:40960
	s_waitcnt lgkmcnt(4)
	v_mfma_f32_32x32x16_bf16 v[164:179], v[132:135], v[140:143], v[164:179]
	s_add_u32 m0, s22, 0x8000
	s_nop 0
	global_load_lds_dwordx4 v[244:245], off
	v_lshl_add_u64 v[244:245], v[244:245], 0, s[98:99]
	v_mfma_f32_32x32x16_bf16 v[180:195], v[132:135], v[144:147], v[180:195]
	s_add_u32 m0, s22, 0x9000
	s_nop 0
	global_load_lds_dwordx4 v[246:247], off
	v_lshl_add_u64 v[246:247], v[246:247], 0, s[98:99]
	v_mfma_f32_32x32x16_bf16 v[206:221], v[136:139], v[140:143], v[206:221]
	v_mfma_f32_32x32x16_bf16 v[222:237], v[136:139], v[144:147], v[222:237]
	ds_read_b128 v[132:135], v122 offset:16384
	ds_read_b128 v[136:139], v122 offset:20480
	ds_read_b128 v[140:143], v126 offset:32768
	ds_read_b128 v[144:147], v126 offset:40960
	s_waitcnt lgkmcnt(4)
	v_mfma_f32_32x32x16_bf16 v[164:179], v[148:151], v[156:159], v[164:179]
	s_add_u32 m0, s22, 0xa000
	s_nop 0
	global_load_lds_dwordx4 v[248:249], off
	v_lshl_add_u64 v[248:249], v[248:249], 0, s[98:99]
	v_mfma_f32_32x32x16_bf16 v[180:195], v[148:151], v[160:163], v[180:195]
	v_mfma_f32_32x32x16_bf16 v[206:221], v[152:155], v[156:159], v[206:221]
	v_mfma_f32_32x32x16_bf16 v[222:237], v[152:155], v[160:163], v[222:237]
	ds_read_b128 v[148:151], v123 offset:16384
	ds_read_b128 v[152:155], v123 offset:20480
	ds_read_b128 v[156:159], v127 offset:32768
	ds_read_b128 v[160:163], v127 offset:40960
	s_waitcnt lgkmcnt(4)
	v_mfma_f32_32x32x16_bf16 v[164:179], v[132:135], v[140:143], v[164:179]
	s_add_u32 m0, s22, 0xb000
	s_nop 0
	global_load_lds_dwordx4 v[250:251], off
	v_lshl_add_u64 v[250:251], v[250:251], 0, s[98:99]
	v_mfma_f32_32x32x16_bf16 v[180:195], v[132:135], v[144:147], v[180:195]
	v_mfma_f32_32x32x16_bf16 v[206:221], v[136:139], v[140:143], v[206:221]
	v_mfma_f32_32x32x16_bf16 v[222:237], v[136:139], v[144:147], v[222:237]
	s_waitcnt vmcnt(4) lgkmcnt(0)
	s_barrier
	ds_read_b128 v[132:135], v120
	ds_read_b128 v[136:139], v120 offset:4096
	ds_read_b128 v[140:143], v124 offset:49152
	ds_read_b128 v[144:147], v124 offset:57344
	v_mfma_f32_32x32x16_bf16 v[164:179], v[148:151], v[156:159], v[164:179]
	v_mfma_f32_32x32x16_bf16 v[180:195], v[148:151], v[160:163], v[180:195]
	v_mfma_f32_32x32x16_bf16 v[206:221], v[152:155], v[156:159], v[206:221]
	v_mfma_f32_32x32x16_bf16 v[222:237], v[152:155], v[160:163], v[222:237]
	ds_read_b128 v[148:151], v121
	ds_read_b128 v[152:155], v121 offset:4096
	ds_read_b128 v[156:159], v125 offset:49152
	ds_read_b128 v[160:163], v125 offset:57344
	s_waitcnt lgkmcnt(4)
	v_mfma_f32_32x32x16_bf16 v[50:65], v[132:135], v[140:143], v[50:65]
	s_add_u32 m0, s22, 0xc000
	s_nop 0
	global_load_lds_dwordx4 v[70:71], off
	v_lshl_add_u64 v[70:71], v[70:71], 0, s[98:99]
	v_mfma_f32_32x32x16_bf16 v[34:49], v[132:135], v[144:147], v[34:49]
	s_add_u32 m0, s22, 0x4000
	s_nop 0
	global_load_lds_dwordx4 v[78:79], off
	v_lshl_add_u64 v[78:79], v[78:79], 0, s[98:99]
	v_mfma_f32_32x32x16_bf16 v[18:33], v[136:139], v[140:143], v[18:33]
	s_add_u32 m0, s22, 0xd000
	s_nop 0
	global_load_lds_dwordx4 v[72:73], off
	v_lshl_add_u64 v[72:73], v[72:73], 0, s[98:99]
	v_mfma_f32_32x32x16_bf16 v[2:17], v[136:139], v[144:147], v[2:17]
	ds_read_b128 v[132:135], v122
	ds_read_b128 v[136:139], v122 offset:4096
	ds_read_b128 v[140:143], v126 offset:49152
	ds_read_b128 v[144:147], v126 offset:57344
	s_waitcnt lgkmcnt(4)
	v_mfma_f32_32x32x16_bf16 v[50:65], v[148:151], v[156:159], v[50:65]
	s_add_u32 m0, s22, 0x5000
	s_nop 0
	global_load_lds_dwordx4 v[238:239], off
	v_lshl_add_u64 v[238:239], v[238:239], 0, s[98:99]
	v_mfma_f32_32x32x16_bf16 v[34:49], v[148:151], v[160:163], v[34:49]
	s_add_u32 m0, s22, 0xe000
	s_nop 0
	global_load_lds_dwordx4 v[74:75], off
	v_lshl_add_u64 v[74:75], v[74:75], 0, s[98:99]
	v_mfma_f32_32x32x16_bf16 v[18:33], v[152:155], v[156:159], v[18:33]
	s_add_u32 m0, s22, 0x6000
	s_nop 0
	global_load_lds_dwordx4 v[240:241], off
	v_lshl_add_u64 v[240:241], v[240:241], 0, s[98:99]
	v_mfma_f32_32x32x16_bf16 v[2:17], v[152:155], v[160:163], v[2:17]
	ds_read_b128 v[148:151], v123
	ds_read_b128 v[152:155], v123 offset:4096
	ds_read_b128 v[156:159], v127 offset:49152
	ds_read_b128 v[160:163], v127 offset:57344
	s_waitcnt lgkmcnt(4)
	v_mfma_f32_32x32x16_bf16 v[50:65], v[132:135], v[140:143], v[50:65]
	s_add_u32 m0, s22, 0xf000
	s_nop 0
	global_load_lds_dwordx4 v[76:77], off
	v_lshl_add_u64 v[76:77], v[76:77], 0, s[98:99]
	v_mfma_f32_32x32x16_bf16 v[34:49], v[132:135], v[144:147], v[34:49]
	s_add_u32 m0, s22, 0x7000
	s_nop 0
	global_load_lds_dwordx4 v[242:243], off
	v_lshl_add_u64 v[242:243], v[242:243], 0, s[98:99]
	v_mfma_f32_32x32x16_bf16 v[18:33], v[136:139], v[140:143], v[18:33]
	v_mfma_f32_32x32x16_bf16 v[2:17], v[136:139], v[144:147], v[2:17]
	s_waitcnt vmcnt(8) lgkmcnt(0)
	s_barrier
	ds_read_b128 v[132:135], v120
	ds_read_b128 v[136:139], v120 offset:4096
	ds_read_b128 v[140:143], v124 offset:16384
	ds_read_b128 v[144:147], v124 offset:24576
	v_mfma_f32_32x32x16_bf16 v[50:65], v[148:151], v[156:159], v[50:65]
	v_mfma_f32_32x32x16_bf16 v[34:49], v[148:151], v[160:163], v[34:49]
	v_mfma_f32_32x32x16_bf16 v[18:33], v[152:155], v[156:159], v[18:33]
	v_mfma_f32_32x32x16_bf16 v[2:17], v[152:155], v[160:163], v[2:17]
	ds_read_b128 v[148:151], v121
	ds_read_b128 v[152:155], v121 offset:4096
	ds_read_b128 v[156:159], v125 offset:16384
	ds_read_b128 v[160:163], v125 offset:24576
	s_waitcnt lgkmcnt(4)
	v_mfma_f32_32x32x16_bf16 v[164:179], v[132:135], v[140:143], v[164:179]
	s_add_u32 m0, s22, 0x10000
	s_nop 0
	global_load_lds_dwordx4 v[244:245], off
	v_lshl_add_u64 v[244:245], v[244:245], 0, s[98:99]
	v_mfma_f32_32x32x16_bf16 v[180:195], v[132:135], v[144:147], v[180:195]
	s_add_u32 m0, s22, 0x11000
	s_nop 0
	global_load_lds_dwordx4 v[246:247], off
	v_lshl_add_u64 v[246:247], v[246:247], 0, s[98:99]
	v_mfma_f32_32x32x16_bf16 v[206:221], v[136:139], v[140:143], v[206:221]
	v_mfma_f32_32x32x16_bf16 v[222:237], v[136:139], v[144:147], v[222:237]
	ds_read_b128 v[132:135], v122
	ds_read_b128 v[136:139], v122 offset:4096
	ds_read_b128 v[140:143], v126 offset:16384
	ds_read_b128 v[144:147], v126 offset:24576
	s_waitcnt lgkmcnt(4)
	v_mfma_f32_32x32x16_bf16 v[164:179], v[148:151], v[156:159], v[164:179]
	s_add_u32 m0, s22, 0x12000
	s_nop 0
	global_load_lds_dwordx4 v[248:249], off
	v_lshl_add_u64 v[248:249], v[248:249], 0, s[98:99]
	v_mfma_f32_32x32x16_bf16 v[180:195], v[148:151], v[160:163], v[180:195]
	v_mfma_f32_32x32x16_bf16 v[206:221], v[152:155], v[156:159], v[206:221]
	v_mfma_f32_32x32x16_bf16 v[222:237], v[152:155], v[160:163], v[222:237]
	ds_read_b128 v[148:151], v123
	ds_read_b128 v[152:155], v123 offset:4096
	ds_read_b128 v[156:159], v127 offset:16384
	ds_read_b128 v[160:163], v127 offset:24576
	s_waitcnt lgkmcnt(4)
	v_mfma_f32_32x32x16_bf16 v[164:179], v[132:135], v[140:143], v[164:179]
	s_add_u32 m0, s22, 0x13000
	s_nop 0
	global_load_lds_dwordx4 v[250:251], off
	v_lshl_add_u64 v[250:251], v[250:251], 0, s[98:99]
	v_mfma_f32_32x32x16_bf16 v[180:195], v[132:135], v[144:147], v[180:195]
	v_mfma_f32_32x32x16_bf16 v[206:221], v[136:139], v[140:143], v[206:221]
	v_mfma_f32_32x32x16_bf16 v[222:237], v[136:139], v[144:147], v[222:237]
	s_waitcnt vmcnt(4) lgkmcnt(0)
	s_barrier
	ds_read_b128 v[132:135], v120 offset:16384
	ds_read_b128 v[136:139], v120 offset:20480
	ds_read_b128 v[140:143], v124 offset:32768
	ds_read_b128 v[144:147], v124 offset:40960
	v_mfma_f32_32x32x16_bf16 v[164:179], v[148:151], v[156:159], v[164:179]
	v_mfma_f32_32x32x16_bf16 v[180:195], v[148:151], v[160:163], v[180:195]
	v_mfma_f32_32x32x16_bf16 v[206:221], v[152:155], v[156:159], v[206:221]
	v_mfma_f32_32x32x16_bf16 v[222:237], v[152:155], v[160:163], v[222:237]
	ds_read_b128 v[148:151], v121 offset:16384
	ds_read_b128 v[152:155], v121 offset:20480
	ds_read_b128 v[156:159], v125 offset:32768
	ds_read_b128 v[160:163], v125 offset:40960
	s_waitcnt lgkmcnt(4)
	v_mfma_f32_32x32x16_bf16 v[50:65], v[132:135], v[140:143], v[50:65]
	s_add_u32 m0, s22, 0x8000
	s_nop 0
	global_load_lds_dwordx4 v[70:71], off
	v_lshl_add_u64 v[70:71], v[70:71], 0, s[98:99]
	v_mfma_f32_32x32x16_bf16 v[34:49], v[132:135], v[144:147], v[34:49]
	s_mov_b32 m0, s22
	s_nop 0
	global_load_lds_dwordx4 v[78:79], off
	v_lshl_add_u64 v[78:79], v[78:79], 0, s[98:99]
	v_mfma_f32_32x32x16_bf16 v[18:33], v[136:139], v[140:143], v[18:33]
	s_add_u32 m0, s22, 0x9000
	s_nop 0
	global_load_lds_dwordx4 v[72:73], off
	v_lshl_add_u64 v[72:73], v[72:73], 0, s[98:99]
	v_mfma_f32_32x32x16_bf16 v[2:17], v[136:139], v[144:147], v[2:17]
	ds_read_b128 v[132:135], v122 offset:16384
	ds_read_b128 v[136:139], v122 offset:20480
	ds_read_b128 v[140:143], v126 offset:32768
	ds_read_b128 v[144:147], v126 offset:40960
	s_waitcnt lgkmcnt(4)
	v_mfma_f32_32x32x16_bf16 v[50:65], v[148:151], v[156:159], v[50:65]
	s_add_u32 m0, s22, 0x1000
	s_nop 0
	global_load_lds_dwordx4 v[238:239], off
	v_lshl_add_u64 v[238:239], v[238:239], 0, s[98:99]
	v_mfma_f32_32x32x16_bf16 v[34:49], v[148:151], v[160:163], v[34:49]
	s_add_u32 m0, s22, 0xa000
	s_nop 0
	global_load_lds_dwordx4 v[74:75], off
	v_lshl_add_u64 v[74:75], v[74:75], 0, s[98:99]
	v_mfma_f32_32x32x16_bf16 v[18:33], v[152:155], v[156:159], v[18:33]
	s_add_u32 m0, s22, 0x2000
	s_nop 0
	global_load_lds_dwordx4 v[240:241], off
	v_lshl_add_u64 v[240:241], v[240:241], 0, s[98:99]
	v_mfma_f32_32x32x16_bf16 v[2:17], v[152:155], v[160:163], v[2:17]
	ds_read_b128 v[148:151], v123 offset:16384
	ds_read_b128 v[152:155], v123 offset:20480
	ds_read_b128 v[156:159], v127 offset:32768
	ds_read_b128 v[160:163], v127 offset:40960
	s_waitcnt lgkmcnt(4)
	v_mfma_f32_32x32x16_bf16 v[50:65], v[132:135], v[140:143], v[50:65]
	s_add_u32 m0, s22, 0xb000
	s_nop 0
	global_load_lds_dwordx4 v[76:77], off
	v_lshl_add_u64 v[76:77], v[76:77], 0, s[98:99]
	v_mfma_f32_32x32x16_bf16 v[34:49], v[132:135], v[144:147], v[34:49]
	s_add_u32 m0, s22, 0x3000
	s_nop 0
	global_load_lds_dwordx4 v[242:243], off
	v_lshl_add_u64 v[242:243], v[242:243], 0, s[98:99]
	v_mfma_f32_32x32x16_bf16 v[18:33], v[136:139], v[140:143], v[18:33]
	v_mfma_f32_32x32x16_bf16 v[2:17], v[136:139], v[144:147], v[2:17]
	s_waitcnt vmcnt(8) lgkmcnt(0)
	s_barrier
	ds_read_b128 v[132:135], v120 offset:16384
	ds_read_b128 v[136:139], v120 offset:20480
	ds_read_b128 v[140:143], v124 offset:49152
	ds_read_b128 v[144:147], v124 offset:57344
	v_mfma_f32_32x32x16_bf16 v[50:65], v[148:151], v[156:159], v[50:65]
	v_mfma_f32_32x32x16_bf16 v[34:49], v[148:151], v[160:163], v[34:49]
	v_mfma_f32_32x32x16_bf16 v[18:33], v[152:155], v[156:159], v[18:33]
	v_mfma_f32_32x32x16_bf16 v[2:17], v[152:155], v[160:163], v[2:17]
	ds_read_b128 v[148:151], v121 offset:16384
	ds_read_b128 v[152:155], v121 offset:20480
	ds_read_b128 v[156:159], v125 offset:49152
	ds_read_b128 v[160:163], v125 offset:57344
	s_waitcnt lgkmcnt(4)
	v_mfma_f32_32x32x16_bf16 v[164:179], v[132:135], v[140:143], v[164:179]
	s_add_u32 m0, s22, 0xc000
	s_nop 0
	global_load_lds_dwordx4 v[244:245], off
	v_lshl_add_u64 v[244:245], v[244:245], 0, s[98:99]
	v_mfma_f32_32x32x16_bf16 v[180:195], v[132:135], v[144:147], v[180:195]
	s_add_u32 m0, s22, 0xd000
	s_nop 0
	global_load_lds_dwordx4 v[246:247], off
	v_lshl_add_u64 v[246:247], v[246:247], 0, s[98:99]
	v_mfma_f32_32x32x16_bf16 v[206:221], v[136:139], v[140:143], v[206:221]
	v_mfma_f32_32x32x16_bf16 v[222:237], v[136:139], v[144:147], v[222:237]
	ds_read_b128 v[132:135], v122 offset:16384
	ds_read_b128 v[136:139], v122 offset:20480
	ds_read_b128 v[140:143], v126 offset:49152
	ds_read_b128 v[144:147], v126 offset:57344
	s_waitcnt lgkmcnt(4)
	v_mfma_f32_32x32x16_bf16 v[164:179], v[148:151], v[156:159], v[164:179]
	s_add_u32 m0, s22, 0xe000
	s_nop 0
	global_load_lds_dwordx4 v[248:249], off
	v_lshl_add_u64 v[248:249], v[248:249], 0, s[98:99]
	v_mfma_f32_32x32x16_bf16 v[180:195], v[148:151], v[160:163], v[180:195]
	v_mfma_f32_32x32x16_bf16 v[206:221], v[152:155], v[156:159], v[206:221]
	v_mfma_f32_32x32x16_bf16 v[222:237], v[152:155], v[160:163], v[222:237]
	ds_read_b128 v[148:151], v123 offset:16384
	ds_read_b128 v[152:155], v123 offset:20480
	ds_read_b128 v[156:159], v127 offset:49152
	ds_read_b128 v[160:163], v127 offset:57344
	s_waitcnt lgkmcnt(4)
	v_mfma_f32_32x32x16_bf16 v[164:179], v[132:135], v[140:143], v[164:179]
	s_add_u32 m0, s22, 0xf000
	s_nop 0
	global_load_lds_dwordx4 v[250:251], off
	v_lshl_add_u64 v[250:251], v[250:251], 0, s[98:99]
	v_mfma_f32_32x32x16_bf16 v[180:195], v[132:135], v[144:147], v[180:195]
	v_mfma_f32_32x32x16_bf16 v[206:221], v[136:139], v[140:143], v[206:221]
	v_mfma_f32_32x32x16_bf16 v[222:237], v[136:139], v[144:147], v[222:237]
	s_waitcnt vmcnt(4) lgkmcnt(0)
	s_barrier
	ds_read_b128 v[132:135], v120
	ds_read_b128 v[136:139], v120 offset:4096
	ds_read_b128 v[140:143], v124 offset:16384
	ds_read_b128 v[144:147], v124 offset:24576
	v_mfma_f32_32x32x16_bf16 v[164:179], v[148:151], v[156:159], v[164:179]
	v_mfma_f32_32x32x16_bf16 v[180:195], v[148:151], v[160:163], v[180:195]
	v_mfma_f32_32x32x16_bf16 v[206:221], v[152:155], v[156:159], v[206:221]
	v_mfma_f32_32x32x16_bf16 v[222:237], v[152:155], v[160:163], v[222:237]
	ds_read_b128 v[148:151], v121
	ds_read_b128 v[152:155], v121 offset:4096
	ds_read_b128 v[156:159], v125 offset:16384
	ds_read_b128 v[160:163], v125 offset:24576
	s_waitcnt lgkmcnt(4)
	v_mfma_f32_32x32x16_bf16 v[50:65], v[132:135], v[140:143], v[50:65]
	s_add_u32 m0, s22, 0x10000
	s_nop 0
	global_load_lds_dwordx4 v[70:71], off
	v_lshl_add_u64 v[70:71], v[70:71], 0, s[98:99]
	v_mfma_f32_32x32x16_bf16 v[34:49], v[132:135], v[144:147], v[34:49]
	s_add_u32 m0, s22, 0x4000
	s_nop 0
	global_load_lds_dwordx4 v[78:79], off
	v_lshl_add_u64 v[78:79], v[78:79], 0, s[98:99]
	v_mfma_f32_32x32x16_bf16 v[18:33], v[136:139], v[140:143], v[18:33]
	s_add_u32 m0, s22, 0x11000
	s_nop 0
	global_load_lds_dwordx4 v[72:73], off
	v_lshl_add_u64 v[72:73], v[72:73], 0, s[98:99]
	v_mfma_f32_32x32x16_bf16 v[2:17], v[136:139], v[144:147], v[2:17]
	ds_read_b128 v[132:135], v122
	ds_read_b128 v[136:139], v122 offset:4096
	ds_read_b128 v[140:143], v126 offset:16384
	ds_read_b128 v[144:147], v126 offset:24576
	s_waitcnt lgkmcnt(4)
	v_mfma_f32_32x32x16_bf16 v[50:65], v[148:151], v[156:159], v[50:65]
	s_add_u32 m0, s22, 0x5000
	s_nop 0
	global_load_lds_dwordx4 v[238:239], off
	v_lshl_add_u64 v[238:239], v[238:239], 0, s[98:99]
	v_mfma_f32_32x32x16_bf16 v[34:49], v[148:151], v[160:163], v[34:49]
	s_add_u32 m0, s22, 0x12000
	s_nop 0
	global_load_lds_dwordx4 v[74:75], off
	v_lshl_add_u64 v[74:75], v[74:75], 0, s[98:99]
	v_mfma_f32_32x32x16_bf16 v[18:33], v[152:155], v[156:159], v[18:33]
	s_add_u32 m0, s22, 0x6000
	s_nop 0
	global_load_lds_dwordx4 v[240:241], off
	v_lshl_add_u64 v[240:241], v[240:241], 0, s[98:99]
	v_mfma_f32_32x32x16_bf16 v[2:17], v[152:155], v[160:163], v[2:17]
	ds_read_b128 v[148:151], v123
	ds_read_b128 v[152:155], v123 offset:4096
	ds_read_b128 v[156:159], v127 offset:16384
	ds_read_b128 v[160:163], v127 offset:24576
	s_waitcnt lgkmcnt(4)
	v_mfma_f32_32x32x16_bf16 v[50:65], v[132:135], v[140:143], v[50:65]
	s_add_u32 m0, s22, 0x13000
	s_nop 0
	global_load_lds_dwordx4 v[76:77], off
	v_lshl_add_u64 v[76:77], v[76:77], 0, s[98:99]
	v_mfma_f32_32x32x16_bf16 v[34:49], v[132:135], v[144:147], v[34:49]
	s_add_u32 m0, s22, 0x7000
	s_nop 0
	global_load_lds_dwordx4 v[242:243], off
	v_lshl_add_u64 v[242:243], v[242:243], 0, s[98:99]
	v_mfma_f32_32x32x16_bf16 v[18:33], v[136:139], v[140:143], v[18:33]
	v_mfma_f32_32x32x16_bf16 v[2:17], v[136:139], v[144:147], v[2:17]
	s_waitcnt vmcnt(8) lgkmcnt(0)
	s_barrier
	ds_read_b128 v[132:135], v120
	ds_read_b128 v[136:139], v120 offset:4096
	ds_read_b128 v[140:143], v124 offset:32768
	ds_read_b128 v[144:147], v124 offset:40960
	v_mfma_f32_32x32x16_bf16 v[50:65], v[148:151], v[156:159], v[50:65]
	v_mfma_f32_32x32x16_bf16 v[34:49], v[148:151], v[160:163], v[34:49]
	v_mfma_f32_32x32x16_bf16 v[18:33], v[152:155], v[156:159], v[18:33]
	v_mfma_f32_32x32x16_bf16 v[2:17], v[152:155], v[160:163], v[2:17]
	ds_read_b128 v[148:151], v121
	ds_read_b128 v[152:155], v121 offset:4096
	ds_read_b128 v[156:159], v125 offset:32768
	ds_read_b128 v[160:163], v125 offset:40960
	s_waitcnt lgkmcnt(4)
	v_mfma_f32_32x32x16_bf16 v[164:179], v[132:135], v[140:143], v[164:179]
	s_add_u32 m0, s22, 0x8000
	s_nop 0
	global_load_lds_dwordx4 v[244:245], off
	v_lshl_add_u64 v[244:245], v[244:245], 0, s[98:99]
	v_mfma_f32_32x32x16_bf16 v[180:195], v[132:135], v[144:147], v[180:195]
	s_add_u32 m0, s22, 0x9000
	s_nop 0
	global_load_lds_dwordx4 v[246:247], off
	v_lshl_add_u64 v[246:247], v[246:247], 0, s[98:99]
	v_mfma_f32_32x32x16_bf16 v[206:221], v[136:139], v[140:143], v[206:221]
	v_mfma_f32_32x32x16_bf16 v[222:237], v[136:139], v[144:147], v[222:237]
	ds_read_b128 v[132:135], v122
	ds_read_b128 v[136:139], v122 offset:4096
	ds_read_b128 v[140:143], v126 offset:32768
	ds_read_b128 v[144:147], v126 offset:40960
	s_waitcnt lgkmcnt(4)
	v_mfma_f32_32x32x16_bf16 v[164:179], v[148:151], v[156:159], v[164:179]
	s_add_u32 m0, s22, 0xa000
	s_nop 0
	global_load_lds_dwordx4 v[248:249], off
	v_lshl_add_u64 v[248:249], v[248:249], 0, s[98:99]
	v_mfma_f32_32x32x16_bf16 v[180:195], v[148:151], v[160:163], v[180:195]
	v_mfma_f32_32x32x16_bf16 v[206:221], v[152:155], v[156:159], v[206:221]
	v_mfma_f32_32x32x16_bf16 v[222:237], v[152:155], v[160:163], v[222:237]
	ds_read_b128 v[148:151], v123
	ds_read_b128 v[152:155], v123 offset:4096
	ds_read_b128 v[156:159], v127 offset:32768
	ds_read_b128 v[160:163], v127 offset:40960
	s_waitcnt lgkmcnt(4)
	v_mfma_f32_32x32x16_bf16 v[164:179], v[132:135], v[140:143], v[164:179]
	s_add_u32 m0, s22, 0xb000
	s_nop 0
	global_load_lds_dwordx4 v[250:251], off
	v_lshl_add_u64 v[250:251], v[250:251], 0, s[98:99]
	v_mfma_f32_32x32x16_bf16 v[180:195], v[132:135], v[144:147], v[180:195]
	v_mfma_f32_32x32x16_bf16 v[206:221], v[136:139], v[140:143], v[206:221]
	v_mfma_f32_32x32x16_bf16 v[222:237], v[136:139], v[144:147], v[222:237]
	s_waitcnt vmcnt(4) lgkmcnt(0)
	s_barrier
	ds_read_b128 v[132:135], v120 offset:16384
	ds_read_b128 v[136:139], v120 offset:20480
	ds_read_b128 v[140:143], v124 offset:49152
	ds_read_b128 v[144:147], v124 offset:57344
	v_mfma_f32_32x32x16_bf16 v[164:179], v[148:151], v[156:159], v[164:179]
	v_mfma_f32_32x32x16_bf16 v[180:195], v[148:151], v[160:163], v[180:195]
	v_mfma_f32_32x32x16_bf16 v[206:221], v[152:155], v[156:159], v[206:221]
	v_mfma_f32_32x32x16_bf16 v[222:237], v[152:155], v[160:163], v[222:237]
	ds_read_b128 v[148:151], v121 offset:16384
	ds_read_b128 v[152:155], v121 offset:20480
	ds_read_b128 v[156:159], v125 offset:49152
	ds_read_b128 v[160:163], v125 offset:57344
	s_waitcnt lgkmcnt(4)
	v_mfma_f32_32x32x16_bf16 v[50:65], v[132:135], v[140:143], v[50:65]
	s_add_u32 m0, s22, 0xc000
	s_nop 0
	global_load_lds_dwordx4 v[70:71], off
	v_lshl_add_u64 v[70:71], v[70:71], 0, s[98:99]
	v_mfma_f32_32x32x16_bf16 v[34:49], v[132:135], v[144:147], v[34:49]
	s_mov_b32 m0, s22
	s_nop 0
	global_load_lds_dwordx4 v[78:79], off
	v_lshl_add_u64 v[78:79], v[78:79], 0, s[98:99]
	v_mfma_f32_32x32x16_bf16 v[18:33], v[136:139], v[140:143], v[18:33]
	s_add_u32 m0, s22, 0xd000
	s_nop 0
	global_load_lds_dwordx4 v[72:73], off
	v_lshl_add_u64 v[72:73], v[72:73], 0, s[98:99]
	v_mfma_f32_32x32x16_bf16 v[2:17], v[136:139], v[144:147], v[2:17]
	ds_read_b128 v[132:135], v122 offset:16384
	ds_read_b128 v[136:139], v122 offset:20480
	ds_read_b128 v[140:143], v126 offset:49152
	ds_read_b128 v[144:147], v126 offset:57344
	s_waitcnt lgkmcnt(4)
	v_mfma_f32_32x32x16_bf16 v[50:65], v[148:151], v[156:159], v[50:65]
	s_add_u32 m0, s22, 0x1000
	s_nop 0
	global_load_lds_dwordx4 v[238:239], off
	v_lshl_add_u64 v[238:239], v[238:239], 0, s[98:99]
	v_mfma_f32_32x32x16_bf16 v[34:49], v[148:151], v[160:163], v[34:49]
	s_add_u32 m0, s22, 0xe000
	s_nop 0
	global_load_lds_dwordx4 v[74:75], off
	v_lshl_add_u64 v[74:75], v[74:75], 0, s[98:99]
	v_mfma_f32_32x32x16_bf16 v[18:33], v[152:155], v[156:159], v[18:33]
	s_add_u32 m0, s22, 0x2000
	s_nop 0
	global_load_lds_dwordx4 v[240:241], off
	v_lshl_add_u64 v[240:241], v[240:241], 0, s[98:99]
	v_mfma_f32_32x32x16_bf16 v[2:17], v[152:155], v[160:163], v[2:17]
	ds_read_b128 v[148:151], v123 offset:16384
	ds_read_b128 v[152:155], v123 offset:20480
	ds_read_b128 v[156:159], v127 offset:49152
	ds_read_b128 v[160:163], v127 offset:57344
	s_waitcnt lgkmcnt(4)
	v_mfma_f32_32x32x16_bf16 v[50:65], v[132:135], v[140:143], v[50:65]
	s_add_u32 m0, s22, 0xf000
	s_nop 0
	global_load_lds_dwordx4 v[76:77], off
	v_lshl_add_u64 v[76:77], v[76:77], 0, s[98:99]
	v_mfma_f32_32x32x16_bf16 v[34:49], v[132:135], v[144:147], v[34:49]
	s_add_u32 m0, s22, 0x3000
	s_nop 0
	global_load_lds_dwordx4 v[242:243], off
	v_lshl_add_u64 v[242:243], v[242:243], 0, s[98:99]
	v_mfma_f32_32x32x16_bf16 v[18:33], v[136:139], v[140:143], v[18:33]
	v_mfma_f32_32x32x16_bf16 v[2:17], v[136:139], v[144:147], v[2:17]
	s_waitcnt vmcnt(8) lgkmcnt(0)
	s_barrier
	ds_read_b128 v[132:135], v120 offset:16384
	ds_read_b128 v[136:139], v120 offset:20480
	ds_read_b128 v[140:143], v124 offset:16384
	ds_read_b128 v[144:147], v124 offset:24576
	v_mfma_f32_32x32x16_bf16 v[50:65], v[148:151], v[156:159], v[50:65]
	v_mfma_f32_32x32x16_bf16 v[34:49], v[148:151], v[160:163], v[34:49]
	v_mfma_f32_32x32x16_bf16 v[18:33], v[152:155], v[156:159], v[18:33]
	v_mfma_f32_32x32x16_bf16 v[2:17], v[152:155], v[160:163], v[2:17]
	ds_read_b128 v[148:151], v121 offset:16384
	ds_read_b128 v[152:155], v121 offset:20480
	ds_read_b128 v[156:159], v125 offset:16384
	ds_read_b128 v[160:163], v125 offset:24576
	s_waitcnt lgkmcnt(4)
	v_mfma_f32_32x32x16_bf16 v[164:179], v[132:135], v[140:143], v[164:179]
	s_add_u32 m0, s22, 0x10000
	s_nop 0
	global_load_lds_dwordx4 v[244:245], off
	v_lshl_add_u64 v[244:245], v[244:245], 0, s[98:99]
	v_mfma_f32_32x32x16_bf16 v[180:195], v[132:135], v[144:147], v[180:195]
	s_add_u32 m0, s22, 0x11000
	s_nop 0
	global_load_lds_dwordx4 v[246:247], off
	v_lshl_add_u64 v[246:247], v[246:247], 0, s[98:99]
	v_mfma_f32_32x32x16_bf16 v[206:221], v[136:139], v[140:143], v[206:221]
	v_mfma_f32_32x32x16_bf16 v[222:237], v[136:139], v[144:147], v[222:237]
	ds_read_b128 v[132:135], v122 offset:16384
	ds_read_b128 v[136:139], v122 offset:20480
	ds_read_b128 v[140:143], v126 offset:16384
	ds_read_b128 v[144:147], v126 offset:24576
	s_waitcnt lgkmcnt(4)
	v_mfma_f32_32x32x16_bf16 v[164:179], v[148:151], v[156:159], v[164:179]
	s_add_u32 m0, s22, 0x12000
	s_nop 0
	global_load_lds_dwordx4 v[248:249], off
	v_lshl_add_u64 v[248:249], v[248:249], 0, s[98:99]
	v_mfma_f32_32x32x16_bf16 v[180:195], v[148:151], v[160:163], v[180:195]
	v_mfma_f32_32x32x16_bf16 v[206:221], v[152:155], v[156:159], v[206:221]
	v_mfma_f32_32x32x16_bf16 v[222:237], v[152:155], v[160:163], v[222:237]
	ds_read_b128 v[148:151], v123 offset:16384
	ds_read_b128 v[152:155], v123 offset:20480
	ds_read_b128 v[156:159], v127 offset:16384
	ds_read_b128 v[160:163], v127 offset:24576
	s_waitcnt lgkmcnt(4)
	v_mfma_f32_32x32x16_bf16 v[164:179], v[132:135], v[140:143], v[164:179]
	s_add_u32 m0, s22, 0x13000
	s_nop 0
	global_load_lds_dwordx4 v[250:251], off
	v_lshl_add_u64 v[250:251], v[250:251], 0, s[98:99]
	v_mfma_f32_32x32x16_bf16 v[180:195], v[132:135], v[144:147], v[180:195]
	v_mfma_f32_32x32x16_bf16 v[206:221], v[136:139], v[140:143], v[206:221]
	v_mfma_f32_32x32x16_bf16 v[222:237], v[136:139], v[144:147], v[222:237]
	s_waitcnt vmcnt(4) lgkmcnt(0)
	s_barrier
	ds_read_b128 v[132:135], v120
	ds_read_b128 v[136:139], v120 offset:4096
	ds_read_b128 v[140:143], v124 offset:32768
	ds_read_b128 v[144:147], v124 offset:40960
	v_mfma_f32_32x32x16_bf16 v[164:179], v[148:151], v[156:159], v[164:179]
	v_mfma_f32_32x32x16_bf16 v[180:195], v[148:151], v[160:163], v[180:195]
	v_mfma_f32_32x32x16_bf16 v[206:221], v[152:155], v[156:159], v[206:221]
	v_mfma_f32_32x32x16_bf16 v[222:237], v[152:155], v[160:163], v[222:237]
	ds_read_b128 v[148:151], v121
	ds_read_b128 v[152:155], v121 offset:4096
	ds_read_b128 v[156:159], v125 offset:32768
	ds_read_b128 v[160:163], v125 offset:40960
	s_waitcnt lgkmcnt(4)
	v_mfma_f32_32x32x16_bf16 v[50:65], v[132:135], v[140:143], v[50:65]
	s_add_u32 m0, s22, 0x8000
	s_nop 0
	global_load_lds_dwordx4 v[70:71], off
	v_lshl_add_u64 v[70:71], v[70:71], 0, s[98:99]
	v_mfma_f32_32x32x16_bf16 v[34:49], v[132:135], v[144:147], v[34:49]
	s_add_u32 m0, s22, 0x4000
	s_nop 0
	global_load_lds_dwordx4 v[78:79], off
	v_lshl_add_u64 v[78:79], v[78:79], 0, s[98:99]
	v_mfma_f32_32x32x16_bf16 v[18:33], v[136:139], v[140:143], v[18:33]
	s_add_u32 m0, s22, 0x9000
	s_nop 0
	global_load_lds_dwordx4 v[72:73], off
	v_lshl_add_u64 v[72:73], v[72:73], 0, s[98:99]
	v_mfma_f32_32x32x16_bf16 v[2:17], v[136:139], v[144:147], v[2:17]
	ds_read_b128 v[132:135], v122
	ds_read_b128 v[136:139], v122 offset:4096
	ds_read_b128 v[140:143], v126 offset:32768
	ds_read_b128 v[144:147], v126 offset:40960
	s_waitcnt lgkmcnt(4)
	v_mfma_f32_32x32x16_bf16 v[50:65], v[148:151], v[156:159], v[50:65]
	s_add_u32 m0, s22, 0x5000
	s_nop 0
	global_load_lds_dwordx4 v[238:239], off
	v_lshl_add_u64 v[238:239], v[238:239], 0, s[98:99]
	v_mfma_f32_32x32x16_bf16 v[34:49], v[148:151], v[160:163], v[34:49]
	s_add_u32 m0, s22, 0xa000
	s_nop 0
	global_load_lds_dwordx4 v[74:75], off
	v_lshl_add_u64 v[74:75], v[74:75], 0, s[98:99]
	v_mfma_f32_32x32x16_bf16 v[18:33], v[152:155], v[156:159], v[18:33]
	s_add_u32 m0, s22, 0x6000
	s_nop 0
	global_load_lds_dwordx4 v[240:241], off
	v_lshl_add_u64 v[240:241], v[240:241], 0, s[98:99]
	v_mfma_f32_32x32x16_bf16 v[2:17], v[152:155], v[160:163], v[2:17]
	ds_read_b128 v[148:151], v123
	ds_read_b128 v[152:155], v123 offset:4096
	ds_read_b128 v[156:159], v127 offset:32768
	ds_read_b128 v[160:163], v127 offset:40960
	s_waitcnt lgkmcnt(4)
	v_mfma_f32_32x32x16_bf16 v[50:65], v[132:135], v[140:143], v[50:65]
	s_add_u32 m0, s22, 0xb000
	s_nop 0
	global_load_lds_dwordx4 v[76:77], off
	v_lshl_add_u64 v[76:77], v[76:77], 0, s[98:99]
	v_mfma_f32_32x32x16_bf16 v[34:49], v[132:135], v[144:147], v[34:49]
	s_add_u32 m0, s22, 0x7000
	s_nop 0
	global_load_lds_dwordx4 v[242:243], off
	v_lshl_add_u64 v[242:243], v[242:243], 0, s[98:99]
	v_mfma_f32_32x32x16_bf16 v[18:33], v[136:139], v[140:143], v[18:33]
	v_mfma_f32_32x32x16_bf16 v[2:17], v[136:139], v[144:147], v[2:17]
	s_waitcnt vmcnt(8) lgkmcnt(0)
	s_barrier
	ds_read_b128 v[132:135], v120
	ds_read_b128 v[136:139], v120 offset:4096
	ds_read_b128 v[140:143], v124 offset:49152
	ds_read_b128 v[144:147], v124 offset:57344
	v_mfma_f32_32x32x16_bf16 v[50:65], v[148:151], v[156:159], v[50:65]
	v_mfma_f32_32x32x16_bf16 v[34:49], v[148:151], v[160:163], v[34:49]
	v_mfma_f32_32x32x16_bf16 v[18:33], v[152:155], v[156:159], v[18:33]
	v_mfma_f32_32x32x16_bf16 v[2:17], v[152:155], v[160:163], v[2:17]
	ds_read_b128 v[148:151], v121
	ds_read_b128 v[152:155], v121 offset:4096
	ds_read_b128 v[156:159], v125 offset:49152
	ds_read_b128 v[160:163], v125 offset:57344
	s_waitcnt lgkmcnt(4)
	v_mfma_f32_32x32x16_bf16 v[164:179], v[132:135], v[140:143], v[164:179]
	s_add_u32 m0, s22, 0xc000
	s_nop 0
	global_load_lds_dwordx4 v[244:245], off
	v_lshl_add_u64 v[244:245], v[244:245], 0, s[98:99]
	v_mfma_f32_32x32x16_bf16 v[180:195], v[132:135], v[144:147], v[180:195]
	s_add_u32 m0, s22, 0xd000
	s_nop 0
	global_load_lds_dwordx4 v[246:247], off
	v_lshl_add_u64 v[246:247], v[246:247], 0, s[98:99]
	v_mfma_f32_32x32x16_bf16 v[206:221], v[136:139], v[140:143], v[206:221]
	v_mfma_f32_32x32x16_bf16 v[222:237], v[136:139], v[144:147], v[222:237]
	ds_read_b128 v[132:135], v122
	ds_read_b128 v[136:139], v122 offset:4096
	ds_read_b128 v[140:143], v126 offset:49152
	ds_read_b128 v[144:147], v126 offset:57344
	s_waitcnt lgkmcnt(4)
	v_mfma_f32_32x32x16_bf16 v[164:179], v[148:151], v[156:159], v[164:179]
	s_add_u32 m0, s22, 0xe000
	s_nop 0
	global_load_lds_dwordx4 v[248:249], off
	v_lshl_add_u64 v[248:249], v[248:249], 0, s[98:99]
	v_mfma_f32_32x32x16_bf16 v[180:195], v[148:151], v[160:163], v[180:195]
	v_mfma_f32_32x32x16_bf16 v[206:221], v[152:155], v[156:159], v[206:221]
	v_mfma_f32_32x32x16_bf16 v[222:237], v[152:155], v[160:163], v[222:237]
	ds_read_b128 v[148:151], v123
	ds_read_b128 v[152:155], v123 offset:4096
	ds_read_b128 v[156:159], v127 offset:49152
	ds_read_b128 v[160:163], v127 offset:57344
	s_waitcnt lgkmcnt(4)
	v_mfma_f32_32x32x16_bf16 v[164:179], v[132:135], v[140:143], v[164:179]
	s_add_u32 m0, s22, 0xf000
	s_nop 0
	global_load_lds_dwordx4 v[250:251], off
	v_lshl_add_u64 v[250:251], v[250:251], 0, s[98:99]
	v_mfma_f32_32x32x16_bf16 v[180:195], v[132:135], v[144:147], v[180:195]
	v_mfma_f32_32x32x16_bf16 v[206:221], v[136:139], v[140:143], v[206:221]
	v_mfma_f32_32x32x16_bf16 v[222:237], v[136:139], v[144:147], v[222:237]
	s_waitcnt vmcnt(4) lgkmcnt(0)
	s_barrier
	ds_read_b128 v[132:135], v120 offset:16384
	ds_read_b128 v[136:139], v120 offset:20480
	ds_read_b128 v[140:143], v124 offset:16384
	ds_read_b128 v[144:147], v124 offset:24576
	v_mfma_f32_32x32x16_bf16 v[164:179], v[148:151], v[156:159], v[164:179]
	v_mfma_f32_32x32x16_bf16 v[180:195], v[148:151], v[160:163], v[180:195]
	v_mfma_f32_32x32x16_bf16 v[206:221], v[152:155], v[156:159], v[206:221]
	v_mfma_f32_32x32x16_bf16 v[222:237], v[152:155], v[160:163], v[222:237]
	ds_read_b128 v[148:151], v121 offset:16384
	ds_read_b128 v[152:155], v121 offset:20480
	ds_read_b128 v[156:159], v125 offset:16384
	ds_read_b128 v[160:163], v125 offset:24576
	s_waitcnt lgkmcnt(4)
	v_mfma_f32_32x32x16_bf16 v[50:65], v[132:135], v[140:143], v[50:65]
	v_mfma_f32_32x32x16_bf16 v[34:49], v[132:135], v[144:147], v[34:49]
	v_mfma_f32_32x32x16_bf16 v[18:33], v[136:139], v[140:143], v[18:33]
	v_mfma_f32_32x32x16_bf16 v[2:17], v[136:139], v[144:147], v[2:17]
	ds_read_b128 v[132:135], v122 offset:16384
	ds_read_b128 v[136:139], v122 offset:20480
	ds_read_b128 v[140:143], v126 offset:16384
	ds_read_b128 v[144:147], v126 offset:24576
	s_waitcnt lgkmcnt(4)
	v_mfma_f32_32x32x16_bf16 v[50:65], v[148:151], v[156:159], v[50:65]
	v_mfma_f32_32x32x16_bf16 v[34:49], v[148:151], v[160:163], v[34:49]
	v_mfma_f32_32x32x16_bf16 v[18:33], v[152:155], v[156:159], v[18:33]
	v_mfma_f32_32x32x16_bf16 v[2:17], v[152:155], v[160:163], v[2:17]
	ds_read_b128 v[148:151], v123 offset:16384
	ds_read_b128 v[152:155], v123 offset:20480
	ds_read_b128 v[156:159], v127 offset:16384
	ds_read_b128 v[160:163], v127 offset:24576
	s_waitcnt lgkmcnt(4)
	v_mfma_f32_32x32x16_bf16 v[50:65], v[132:135], v[140:143], v[50:65]
	v_mfma_f32_32x32x16_bf16 v[34:49], v[132:135], v[144:147], v[34:49]
	v_mfma_f32_32x32x16_bf16 v[18:33], v[136:139], v[140:143], v[18:33]
	v_mfma_f32_32x32x16_bf16 v[2:17], v[136:139], v[144:147], v[2:17]
	s_waitcnt vmcnt(0) lgkmcnt(0)
	s_barrier
	ds_read_b128 v[132:135], v120 offset:16384
	ds_read_b128 v[136:139], v120 offset:20480
	ds_read_b128 v[140:143], v124 offset:32768
	ds_read_b128 v[144:147], v124 offset:40960
	v_mfma_f32_32x32x16_bf16 v[50:65], v[148:151], v[156:159], v[50:65]
	v_mfma_f32_32x32x16_bf16 v[34:49], v[148:151], v[160:163], v[34:49]
	v_mfma_f32_32x32x16_bf16 v[18:33], v[152:155], v[156:159], v[18:33]
	v_mfma_f32_32x32x16_bf16 v[2:17], v[152:155], v[160:163], v[2:17]
	ds_read_b128 v[148:151], v121 offset:16384
	ds_read_b128 v[152:155], v121 offset:20480
	ds_read_b128 v[156:159], v125 offset:32768
	ds_read_b128 v[160:163], v125 offset:40960
	s_waitcnt lgkmcnt(4)
	v_mfma_f32_32x32x16_bf16 v[164:179], v[132:135], v[140:143], v[164:179]
	v_mfma_f32_32x32x16_bf16 v[180:195], v[132:135], v[144:147], v[180:195]
	v_mfma_f32_32x32x16_bf16 v[206:221], v[136:139], v[140:143], v[206:221]
	v_mfma_f32_32x32x16_bf16 v[222:237], v[136:139], v[144:147], v[222:237]
	ds_read_b128 v[132:135], v122 offset:16384
	ds_read_b128 v[136:139], v122 offset:20480
	ds_read_b128 v[140:143], v126 offset:32768
	ds_read_b128 v[144:147], v126 offset:40960
	s_waitcnt lgkmcnt(4)
	v_mfma_f32_32x32x16_bf16 v[164:179], v[148:151], v[156:159], v[164:179]
	v_mfma_f32_32x32x16_bf16 v[180:195], v[148:151], v[160:163], v[180:195]
	v_mfma_f32_32x32x16_bf16 v[206:221], v[152:155], v[156:159], v[206:221]
	v_mfma_f32_32x32x16_bf16 v[222:237], v[152:155], v[160:163], v[222:237]
	ds_read_b128 v[148:151], v123 offset:16384
	ds_read_b128 v[152:155], v123 offset:20480
	ds_read_b128 v[156:159], v127 offset:32768
	ds_read_b128 v[160:163], v127 offset:40960
	s_waitcnt lgkmcnt(4)
	v_mfma_f32_32x32x16_bf16 v[164:179], v[132:135], v[140:143], v[164:179]
	v_mfma_f32_32x32x16_bf16 v[180:195], v[132:135], v[144:147], v[180:195]
	v_mfma_f32_32x32x16_bf16 v[206:221], v[136:139], v[140:143], v[206:221]
	v_mfma_f32_32x32x16_bf16 v[222:237], v[136:139], v[144:147], v[222:237]
	s_waitcnt lgkmcnt(0)
	s_barrier
	v_mfma_f32_32x32x16_bf16 v[164:179], v[148:151], v[156:159], v[164:179]
	v_mfma_f32_32x32x16_bf16 v[180:195], v[148:151], v[160:163], v[180:195]
	v_mfma_f32_32x32x16_bf16 v[206:221], v[152:155], v[156:159], v[206:221]
	v_mfma_f32_32x32x16_bf16 v[222:237], v[152:155], v[160:163], v[222:237]
.Lg0_join:
	s_nop 15
.Lg0_epi:
	v_add_u32_e32 v72, s0, v81
	v_or_b32_e32 v70, s1, v84
	s_movk_i32 s0, 0xa30
	v_or_b32_e32 v133, v72, v82
	v_or_b32_e32 v132, v72, v86
	v_or_b32_e32 v130, v72, v87
	v_or_b32_e32 v129, v72, v88
	v_or_b32_e32 v128, v72, v89
	v_or_b32_e32 v127, v72, v90
	v_or_b32_e32 v125, v72, v91
	v_or_b32_e32 v79, v72, v92
	v_ashrrev_i32_e32 v71, 31, v70
	v_or_b32_e32 v126, v72, v94
	v_or_b32_e32 v124, v72, v95
	v_or_b32_e32 v78, v72, v96
	v_or_b32_e32 v73, v72, v100
	v_cmp_gt_i32_e32 vcc, s0, v70
	v_or_b32_e32 v77, v72, v93
	v_or_b32_e32 v76, v72, v97
	v_or_b32_e32 v75, v72, v98
	v_or_b32_e32 v74, v72, v99
	s_and_saveexec_b64 s[0:1], vcc
	s_cbranch_execz .LBB0_493
	v_lshl_add_u64 v[134:135], v[70:71], 2, s[8:9]
	v_mad_i64_i32 v[136:137], s[4:5], v133, s15, v[134:135]
	s_nop 6
	global_store_dword v[136:137], v50, off sc1
	v_mad_i64_i32 v[136:137], s[4:5], v132, s15, v[134:135]
	global_store_dword v[136:137], v51, off sc1
	v_mad_i64_i32 v[50:51], s[4:5], v130, s15, v[134:135]
	global_store_dword v[50:51], v52, off sc1
	v_mad_i64_i32 v[50:51], s[4:5], v129, s15, v[134:135]
	global_store_dword v[50:51], v53, off sc1
	v_mad_i64_i32 v[50:51], s[4:5], v128, s15, v[134:135]
	global_store_dword v[50:51], v54, off sc1
	v_mad_i64_i32 v[50:51], s[4:5], v127, s15, v[134:135]
	global_store_dword v[50:51], v55, off sc1
	v_mad_i64_i32 v[50:51], s[4:5], v125, s15, v[134:135]
	global_store_dword v[50:51], v56, off sc1
	v_mad_i64_i32 v[50:51], s[4:5], v79, s15, v[134:135]
	global_store_dword v[50:51], v57, off sc1
	v_mad_i64_i32 v[50:51], s[4:5], v77, s15, v[134:135]
	global_store_dword v[50:51], v58, off sc1
	v_mad_i64_i32 v[50:51], s[4:5], v126, s15, v[134:135]
	global_store_dword v[50:51], v59, off sc1
	v_mad_i64_i32 v[50:51], s[4:5], v124, s15, v[134:135]
	global_store_dword v[50:51], v60, off sc1
	v_mad_i64_i32 v[50:51], s[4:5], v78, s15, v[134:135]
	global_store_dword v[50:51], v61, off sc1
	v_mad_i64_i32 v[50:51], s[4:5], v76, s15, v[134:135]
	global_store_dword v[50:51], v62, off sc1
	v_mad_i64_i32 v[50:51], s[4:5], v75, s15, v[134:135]
	global_store_dword v[50:51], v63, off sc1
	v_mad_i64_i32 v[50:51], s[4:5], v74, s15, v[134:135]
	global_store_dword v[50:51], v64, off sc1
	v_mad_i64_i32 v[50:51], s[4:5], v73, s15, v[134:135]
	global_store_dword v[50:51], v65, off sc1
